# static s_setprio 1 for the second wave half in all 5 GEMM K-loops, per-segment prio toggles removed
# speedup vs baseline: 1.0034x; 1.0010x over previous
; #define PG8_STAGE(bufoff, gbase, voff) do { _Pragma("unroll") for (int _i = 0; _i < 2; ++_i) \
;         __builtin_amdgcn_global_load_lds((const unsigned*)((const char*)(gbase) + (voff)[_i]), (LAS unsigned*)(lds + (bufoff) + ldsw + _i * 8192), 16, 0, 0); } while (0)
; #define PG8_LDA(dst, b, h) do { _Pragma("unroll") for (int m = 0; m < 4; ++m) _Pragma("unroll") for (int k = 0; k < 2; ++k) dst[m][k] = *(const LAS bf16x8*)(lds + PG8_SA(b, h) + aoff + m * 2048 + k * 1024); } while (0)
; #define PG8_LDB(dst, b, h) do { _Pragma("unroll") for (int n = 0; n < 2; ++n) _Pragma("unroll") for (int k = 0; k < 2; ++k) dst[n][k] = *(const LAS bf16x8*)(lds + PG8_SB(b, h) + boff + n * 2048 + k * 1024); } while (0)
; #define PG8_WAIT_V(n) asm volatile("s_waitcnt vmcnt(" #n ")" ::: "memory")
; #define PG8_WAIT_L(n) asm volatile("s_waitcnt lgkmcnt(" #n ")" ::: "memory")
; #define PG8_BAR __builtin_amdgcn_s_barrier()
; #define PG8_SCHED __builtin_amdgcn_sched_barrier(0)
; template <class Epi, bool ALIGN_EPI = true, bool SP2 = true>
; __device__ __forceinline__ void gemm_phase(LAS unsigned char* lds, const Gemm g, const Order& S, const Epi& E) {
;     ...
;         const char* nA = has_next ? (const char*)(nxt.z ? g.A1 : g.A0) + (size_t)nxt.pm * tstepA + (size_t)nxt.kt0 * kstep : cA; const char* nB = has_next ? (const char*)(nxt.z ? g.B1 : g.B0) + (size_t)nxt.pn * tstepB + (size_t)nxt.kt0 * kstep : cB;
;         const int nt = cur.nkt;
;         for (int t = 0; t < nt; t += 2) {
;             const bool last = (t == nt - 2);
;             const char* a1 = cA + (size_t)(t + 1) * kstep;
;             const char* a2 = last ? nA : cA + (size_t)(t + 2) * kstep; const char* b2 = last ? nB : cB + (size_t)(t + 2) * kstep;
;             const char* a3 = a2 + kstep; const char* b3 = b2 + kstep;
;             if constexpr (SP2) {
;             PG8_LDB(B0, 0, 0); PG8_LDB(B1, 0, 1); PG8_SCHED; PG8_LDA(At, 0, 0); PG8_STAGE(PG8_SA(1, 1), a1 + hstepA, voffA);
;             PG8_WAIT_V(8); PG8_WAIT_L(0); PG8_BAR; PG8_MMA(0, 0, At, B0); PG8_MMA(0, 1, At, B1); PG8_BAR; PG8_SCHED;
;     ...
;         for (int a = 0; a < 2; ++a)
; #pragma unroll
;             for (int b = 0; b < 2; ++b)
; #pragma unroll
;                 for (int m = 0; m < 4; ++m)
; #pragma unroll
;                     for (int n = 0; n < 2; ++n) acc[a][b][m][n] = (f32x4){0.f, 0.f, 0.f, 0.f};
.LBB0_160:
	s_ashr_i32 s89, s88, 31
	s_lshl_b64 s[50:51], s[88:89], 19
	s_add_u32 s52, s23, s50
	s_addc_u32 s53, s24, s51
	s_and_b64 s[50:51], s[92:93], exec
	s_cselect_b32 s91, s53, s13
	s_cselect_b32 s90, s52, s12
	s_ashr_i32 s87, s86, 31
	s_lshl_b64 s[50:51], s[86:87], 19
	s_add_u32 s52, s60, s50
	s_addc_u32 s53, s61, s51
	s_and_b64 s[50:51], s[92:93], exec
	s_cselect_b32 s93, s53, s15
	s_cselect_b32 s92, s52, s14
	s_add_u32 s12, s12, 0x40080
	s_addc_u32 s13, s13, 0
	s_add_u32 s50, s14, 0x100
	v_mov_b32_e32 v2, 0
	s_addc_u32 s51, s15, 0
	s_mov_b32 s52, -2
	v_mov_b32_e32 v3, v2
	v_mov_b32_e32 v4, v2
	v_mov_b32_e32 v5, v2
	v_mov_b32_e32 v6, v2
	v_mov_b32_e32 v7, v2
	v_mov_b32_e32 v8, v2
	v_mov_b32_e32 v9, v2
	v_mov_b32_e32 v14, v2
	v_mov_b32_e32 v15, v2
	v_mov_b32_e32 v16, v2
	v_mov_b32_e32 v17, v2
	v_mov_b32_e32 v22, v2
	v_mov_b32_e32 v23, v2
	v_mov_b32_e32 v24, v2
	v_mov_b32_e32 v25, v2
	v_mov_b32_e32 v30, v2
	v_mov_b32_e32 v31, v2
	v_mov_b32_e32 v32, v2
	v_mov_b32_e32 v33, v2
	v_mov_b32_e32 v38, v2
	v_mov_b32_e32 v39, v2
	v_mov_b32_e32 v40, v2
	v_mov_b32_e32 v41, v2
	v_mov_b32_e32 v46, v2
	v_mov_b32_e32 v47, v2
	v_mov_b32_e32 v48, v2
	v_mov_b32_e32 v49, v2
	v_mov_b32_e32 v54, v2
	v_mov_b32_e32 v55, v2
	v_mov_b32_e32 v56, v2
	v_mov_b32_e32 v57, v2
	v_mov_b32_e32 v10, v2
	v_mov_b32_e32 v11, v2
	v_mov_b32_e32 v12, v2
	v_mov_b32_e32 v13, v2
	v_mov_b32_e32 v18, v2
	v_mov_b32_e32 v19, v2
	v_mov_b32_e32 v20, v2
	v_mov_b32_e32 v21, v2
	v_mov_b32_e32 v26, v2
	v_mov_b32_e32 v27, v2
	v_mov_b32_e32 v28, v2
	v_mov_b32_e32 v29, v2
	v_mov_b32_e32 v34, v2
	v_mov_b32_e32 v35, v2
	v_mov_b32_e32 v36, v2
	v_mov_b32_e32 v37, v2
	v_mov_b32_e32 v42, v2
	v_mov_b32_e32 v43, v2
	v_mov_b32_e32 v44, v2
	v_mov_b32_e32 v45, v2
	v_mov_b32_e32 v50, v2
	v_mov_b32_e32 v51, v2
	v_mov_b32_e32 v52, v2
	v_mov_b32_e32 v53, v2
	v_mov_b32_e32 v58, v2
	v_mov_b32_e32 v59, v2
	v_mov_b32_e32 v60, v2
	v_mov_b32_e32 v61, v2
	v_mov_b32_e32 v62, v2
	v_mov_b32_e32 v63, v2
	v_mov_b32_e32 v64, v2
	v_mov_b32_e32 v65, v2
	v_mov_b32_e32 v66, v2
	v_mov_b32_e32 v67, v2
	v_mov_b32_e32 v68, v2
	v_mov_b32_e32 v69, v2
	v_mov_b32_e32 v70, v2
	v_mov_b32_e32 v71, v2
	v_mov_b32_e32 v72, v2
	v_mov_b32_e32 v73, v2
	v_mov_b32_e32 v82, v2
	v_mov_b32_e32 v83, v2
	v_mov_b32_e32 v84, v2
	v_mov_b32_e32 v85, v2
	v_mov_b32_e32 v86, v2
	v_mov_b32_e32 v87, v2
	v_mov_b32_e32 v88, v2
	v_mov_b32_e32 v89, v2
	v_mov_b32_e32 v98, v2
	v_mov_b32_e32 v99, v2
	v_mov_b32_e32 v100, v2
	v_mov_b32_e32 v101, v2
	v_mov_b32_e32 v102, v2
	v_mov_b32_e32 v103, v2
	v_mov_b32_e32 v104, v2
	v_mov_b32_e32 v105, v2
	v_mov_b32_e32 v114, v2
	v_mov_b32_e32 v115, v2
	v_mov_b32_e32 v116, v2
	v_mov_b32_e32 v117, v2
	v_mov_b32_e32 v118, v2
	v_mov_b32_e32 v119, v2
	v_mov_b32_e32 v120, v2
	v_mov_b32_e32 v121, v2
	v_mov_b32_e32 v74, v2
	v_mov_b32_e32 v75, v2
	v_mov_b32_e32 v76, v2
	v_mov_b32_e32 v77, v2
	v_mov_b32_e32 v78, v2
	v_mov_b32_e32 v79, v2
	v_mov_b32_e32 v80, v2
	v_mov_b32_e32 v81, v2
	v_mov_b32_e32 v90, v2
	v_mov_b32_e32 v91, v2
	v_mov_b32_e32 v92, v2
	v_mov_b32_e32 v93, v2
	v_mov_b32_e32 v94, v2
	v_mov_b32_e32 v95, v2
	v_mov_b32_e32 v96, v2
	v_mov_b32_e32 v97, v2
	v_mov_b32_e32 v106, v2
	v_mov_b32_e32 v107, v2
	v_mov_b32_e32 v108, v2
	v_mov_b32_e32 v109, v2
	v_mov_b32_e32 v110, v2
	v_mov_b32_e32 v111, v2
	v_mov_b32_e32 v112, v2
	v_mov_b32_e32 v113, v2
	v_mov_b32_e32 v122, v2
	v_mov_b32_e32 v123, v2
	v_mov_b32_e32 v124, v2
	v_mov_b32_e32 v125, v2
	v_mov_b32_e32 v126, v2
	v_mov_b32_e32 v127, v2
	v_mov_b32_e32 v128, v2
	v_mov_b32_e32 v129, v2
	s_cmp_lg_u32 s80, 0
	s_cbranch_scc1 .Lsprio_skip_0
	s_setprio 1
.Lsprio_skip_0:
	.p2align	6
	s_nop 0
	s_nop 0
	s_nop 0
	s_nop 0
	s_nop 0
	s_nop 0
	s_nop 0
	s_nop 0
	s_nop 0
	s_nop 0
	s_nop 0
.LBB0_161:
	s_add_u32 s14, s12, 0xfffc0080
	s_addc_u32 s15, s13, -1
	s_add_i32 s53, 0, 0x10000
	s_cmp_eq_u32 s52, 12
	s_cselect_b32 vcc_hi, s91, s15
	s_cselect_b32 vcc_lo, s90, s14
	v_add_u32_e32 v0, s53, v185
	s_cselect_b32 s15, s93, s51
	s_cselect_b32 s14, s92, s50
	s_add_i32 s58, 0, 0x14000
	ds_read_b128 v[130:133], v0
	ds_read_b128 v[134:137], v0 offset:1024
	ds_read_b128 v[138:141], v0 offset:2048
	ds_read_b128 v[142:145], v0 offset:3072
	v_add_u32_e32 v0, s58, v185
	ds_read_b128 v[146:149], v0
	ds_read_b128 v[150:153], v0 offset:1024
	ds_read_b128 v[154:157], v0 offset:2048
	ds_read_b128 v[158:161], v0 offset:3072
	v_lshl_add_u64 v[202:203], s[12:13], 0, v[172:173]
	s_add_i32 m0, s25, 0xc000
	ds_read_b128 v[176:179], v189
	ds_read_b128 v[180:183], v189 offset:1024
	ds_read_b128 v[190:193], v189 offset:2048
	ds_read_b128 v[194:197], v189 offset:3072
	ds_read_b128 v[198:201], v189 offset:4096
	ds_read_b128 v[224:227], v189 offset:5120
	ds_read_b128 v[228:231], v189 offset:6144
	ds_read_b128 v[232:235], v189 offset:7168
	global_load_lds_dwordx4 v[202:203], off
	v_lshl_add_u64 v[202:203], s[12:13], 0, v[174:175]
	s_add_i32 m0, s25, 0xe000
	s_nop 0
	global_load_lds_dwordx4 v[202:203], off
	s_waitcnt vmcnt(8)
	s_waitcnt lgkmcnt(0)
	s_barrier
; #define PG8_STAGE(bufoff, gbase, voff) do { _Pragma("unroll") for (int _i = 0; _i < 2; ++_i) \
;         __builtin_amdgcn_global_load_lds((const unsigned*)((const char*)(gbase) + (voff)[_i]), (LAS unsigned*)(lds + (bufoff) + ldsw + _i * 8192), 16, 0, 0); } while (0)
; #define PG8_LDA(dst, b, h) do { _Pragma("unroll") for (int m = 0; m < 4; ++m) _Pragma("unroll") for (int k = 0; k < 2; ++k) dst[m][k] = *(const LAS bf16x8*)(lds + PG8_SA(b, h) + aoff + m * 2048 + k * 1024); } while (0)
; #define PG8_LDB(dst, b, h) do { _Pragma("unroll") for (int n = 0; n < 2; ++n) _Pragma("unroll") for (int k = 0; k < 2; ++k) dst[n][k] = *(const LAS bf16x8*)(lds + PG8_SB(b, h) + boff + n * 2048 + k * 1024); } while (0)
; #define PG8_MMA(ai, bj, At, Bt) do { __builtin_amdgcn_s_setprio(1); _Pragma("unroll") for (int m = 0; m < 4; ++m) _Pragma("unroll") for (int n = 0; n < 2; ++n) _Pragma("unroll") for (int k = 0; k < 2; ++k) \
;         acc[ai][bj][m][n] = __builtin_amdgcn_mfma_f32_16x16x32_bf16(Bt[n][k], At[m][k], acc[ai][bj][m][n], 0, 0, 0); __builtin_amdgcn_s_setprio(0); } while (0)
; #define PG8_WAIT_V(n) asm volatile("s_waitcnt vmcnt(" #n ")" ::: "memory")
; #define PG8_WAIT_L(n) asm volatile("s_waitcnt lgkmcnt(" #n ")" ::: "memory")
; #define PG8_BAR __builtin_amdgcn_s_barrier()
; #define PG8_SCHED __builtin_amdgcn_sched_barrier(0)
; template <class Epi, bool ALIGN_EPI = true, bool SP2 = true>
; __device__ __forceinline__ void gemm_phase(LAS unsigned char* lds, const Gemm g, const Order& S, const Epi& E) {
;     ...
;             PG8_LDB(B0, 0, 0); PG8_LDB(B1, 0, 1); PG8_SCHED; PG8_LDA(At, 0, 0); PG8_STAGE(PG8_SA(1, 1), a1 + hstepA, voffA);
;             PG8_WAIT_V(8); PG8_WAIT_L(0); PG8_BAR; PG8_MMA(0, 0, At, B0); PG8_MMA(0, 1, At, B1); PG8_BAR; PG8_SCHED;
;             PG8_LDA(At, 0, 1); PG8_STAGE(PG8_SB(0, 0), b2, voffB); PG8_STAGE(PG8_SB(0, 1), b2 + hstepB, voffB); PG8_STAGE(PG8_SA(0, 0), a2, voffA);
;             PG8_WAIT_V(8); PG8_WAIT_L(0); PG8_BAR; PG8_MMA(1, 0, At, B0); PG8_MMA(1, 1, At, B1); PG8_BAR; PG8_SCHED;
	s_waitcnt lgkmcnt(0)
	v_mfma_f32_16x16x32_bf16 v[126:129], v[130:133], v[176:179], v[126:129]
	v_mfma_f32_16x16x32_bf16 v[122:125], v[138:141], v[176:179], v[122:125]
	v_mfma_f32_16x16x32_bf16 v[110:113], v[130:133], v[190:193], v[110:113]
	v_mfma_f32_16x16x32_bf16 v[106:109], v[138:141], v[190:193], v[106:109]
	v_mfma_f32_16x16x32_bf16 v[94:97], v[130:133], v[198:201], v[94:97]
	v_mfma_f32_16x16x32_bf16 v[90:93], v[138:141], v[198:201], v[90:93]
	v_mfma_f32_16x16x32_bf16 v[78:81], v[130:133], v[228:231], v[78:81]
	v_mfma_f32_16x16x32_bf16 v[74:77], v[138:141], v[228:231], v[74:77]
	v_mfma_f32_16x16x32_bf16 v[126:129], v[134:137], v[180:183], v[126:129]
	v_mfma_f32_16x16x32_bf16 v[122:125], v[142:145], v[180:183], v[122:125]
	v_mfma_f32_16x16x32_bf16 v[110:113], v[134:137], v[194:197], v[110:113]
	v_mfma_f32_16x16x32_bf16 v[106:109], v[142:145], v[194:197], v[106:109]
	v_mfma_f32_16x16x32_bf16 v[94:97], v[134:137], v[224:227], v[94:97]
	v_mfma_f32_16x16x32_bf16 v[90:93], v[142:145], v[224:227], v[90:93]
	v_mfma_f32_16x16x32_bf16 v[78:81], v[134:137], v[232:235], v[78:81]
	v_mfma_f32_16x16x32_bf16 v[74:77], v[142:145], v[232:235], v[74:77]
	v_mfma_f32_16x16x32_bf16 v[118:121], v[146:149], v[176:179], v[118:121]
	v_mfma_f32_16x16x32_bf16 v[114:117], v[154:157], v[176:179], v[114:117]
	v_mfma_f32_16x16x32_bf16 v[102:105], v[146:149], v[190:193], v[102:105]
	v_mfma_f32_16x16x32_bf16 v[98:101], v[154:157], v[190:193], v[98:101]
	v_mfma_f32_16x16x32_bf16 v[86:89], v[146:149], v[198:201], v[86:89]
	v_mfma_f32_16x16x32_bf16 v[82:85], v[154:157], v[198:201], v[82:85]
	v_mfma_f32_16x16x32_bf16 v[70:73], v[146:149], v[228:231], v[70:73]
	v_mfma_f32_16x16x32_bf16 v[66:69], v[154:157], v[228:231], v[66:69]
	v_mfma_f32_16x16x32_bf16 v[118:121], v[150:153], v[180:183], v[118:121]
	v_mfma_f32_16x16x32_bf16 v[114:117], v[158:161], v[180:183], v[114:117]
	v_mfma_f32_16x16x32_bf16 v[102:105], v[150:153], v[194:197], v[102:105]
	v_mfma_f32_16x16x32_bf16 v[98:101], v[158:161], v[194:197], v[98:101]
	v_mfma_f32_16x16x32_bf16 v[86:89], v[150:153], v[224:227], v[86:89]
	v_mfma_f32_16x16x32_bf16 v[82:85], v[158:161], v[224:227], v[82:85]
	v_mfma_f32_16x16x32_bf16 v[70:73], v[150:153], v[232:235], v[70:73]
	v_mfma_f32_16x16x32_bf16 v[66:69], v[158:161], v[232:235], v[66:69]
	s_barrier
	s_add_i32 s53, s53, s21
	v_lshl_add_u64 v[202:203], s[14:15], 0, v[164:165]
	s_mov_b32 m0, s53
	ds_read_b128 v[176:179], v189 offset:16384
	ds_read_b128 v[180:183], v189 offset:17408
	ds_read_b128 v[190:193], v189 offset:18432
	ds_read_b128 v[194:197], v189 offset:19456
	ds_read_b128 v[198:201], v189 offset:20480
	ds_read_b128 v[224:227], v189 offset:21504
	ds_read_b128 v[228:231], v189 offset:22528
	ds_read_b128 v[232:235], v189 offset:23552
	global_load_lds_dwordx4 v[202:203], off
	s_add_i32 m0, s53, 0x2000
	s_add_u32 s54, s14, 0x40000
	v_lshl_add_u64 v[236:237], s[14:15], 0, v[168:169]
	s_addc_u32 s55, s15, 0
	s_add_i32 s53, s58, s21
	global_load_lds_dwordx4 v[236:237], off
	v_lshl_add_u64 v[238:239], s[54:55], 0, v[164:165]
	s_mov_b32 m0, s53
	v_lshl_add_u64 v[240:241], vcc, 0, v[166:167]
	global_load_lds_dwordx4 v[238:239], off
	v_lshl_add_u64 v[238:239], s[54:55], 0, v[168:169]
	s_add_i32 m0, s53, 0x2000
	s_nop 0
	global_load_lds_dwordx4 v[238:239], off
	v_lshl_add_u64 v[238:239], vcc, 0, v[162:163]
	s_mov_b32 m0, s25
	s_nop 0
	global_load_lds_dwordx4 v[238:239], off
	s_mov_b32 m0, s34
	s_nop 0
	global_load_lds_dwordx4 v[240:241], off
	s_waitcnt vmcnt(8)
	s_waitcnt lgkmcnt(0)
	s_barrier
	s_waitcnt lgkmcnt(0)
	v_mfma_f32_16x16x32_bf16 v[62:65], v[130:133], v[176:179], v[62:65]
	v_mfma_f32_16x16x32_bf16 v[58:61], v[138:141], v[176:179], v[58:61]
	v_mfma_f32_16x16x32_bf16 v[50:53], v[130:133], v[190:193], v[50:53]
	v_mfma_f32_16x16x32_bf16 v[42:45], v[138:141], v[190:193], v[42:45]
	v_mfma_f32_16x16x32_bf16 v[34:37], v[130:133], v[198:201], v[34:37]
	v_mfma_f32_16x16x32_bf16 v[26:29], v[138:141], v[198:201], v[26:29]
	v_mfma_f32_16x16x32_bf16 v[18:21], v[130:133], v[228:231], v[18:21]
	v_mfma_f32_16x16x32_bf16 v[10:13], v[138:141], v[228:231], v[10:13]
	v_mfma_f32_16x16x32_bf16 v[62:65], v[134:137], v[180:183], v[62:65]
	v_mfma_f32_16x16x32_bf16 v[58:61], v[142:145], v[180:183], v[58:61]
	v_mfma_f32_16x16x32_bf16 v[50:53], v[134:137], v[194:197], v[50:53]
	v_mfma_f32_16x16x32_bf16 v[42:45], v[142:145], v[194:197], v[42:45]
	v_mfma_f32_16x16x32_bf16 v[34:37], v[134:137], v[224:227], v[34:37]
	v_mfma_f32_16x16x32_bf16 v[26:29], v[142:145], v[224:227], v[26:29]
	v_mfma_f32_16x16x32_bf16 v[18:21], v[134:137], v[232:235], v[18:21]
	v_mfma_f32_16x16x32_bf16 v[10:13], v[142:145], v[232:235], v[10:13]
	v_mfma_f32_16x16x32_bf16 v[54:57], v[146:149], v[176:179], v[54:57]
	v_mfma_f32_16x16x32_bf16 v[46:49], v[154:157], v[176:179], v[46:49]
	v_mfma_f32_16x16x32_bf16 v[38:41], v[146:149], v[190:193], v[38:41]
	v_mfma_f32_16x16x32_bf16 v[30:33], v[154:157], v[190:193], v[30:33]
	v_mfma_f32_16x16x32_bf16 v[22:25], v[146:149], v[198:201], v[22:25]
	v_mfma_f32_16x16x32_bf16 v[14:17], v[154:157], v[198:201], v[14:17]
	v_mfma_f32_16x16x32_bf16 v[6:9], v[146:149], v[228:231], v[6:9]
	v_mfma_f32_16x16x32_bf16 v[2:5], v[154:157], v[228:231], v[2:5]
	v_mfma_f32_16x16x32_bf16 v[54:57], v[150:153], v[180:183], v[54:57]
	v_mfma_f32_16x16x32_bf16 v[46:49], v[158:161], v[180:183], v[46:49]
	v_mfma_f32_16x16x32_bf16 v[38:41], v[150:153], v[194:197], v[38:41]
	v_mfma_f32_16x16x32_bf16 v[30:33], v[158:161], v[194:197], v[30:33]
	v_mfma_f32_16x16x32_bf16 v[22:25], v[150:153], v[224:227], v[22:25]
	v_mfma_f32_16x16x32_bf16 v[14:17], v[158:161], v[224:227], v[14:17]
	v_mfma_f32_16x16x32_bf16 v[6:9], v[150:153], v[232:235], v[6:9]
	v_mfma_f32_16x16x32_bf16 v[2:5], v[158:161], v[232:235], v[2:5]
	s_barrier
; #define PG8_STAGE(bufoff, gbase, voff) do { _Pragma("unroll") for (int _i = 0; _i < 2; ++_i) \
;         __builtin_amdgcn_global_load_lds((const unsigned*)((const char*)(gbase) + (voff)[_i]), (LAS unsigned*)(lds + (bufoff) + ldsw + _i * 8192), 16, 0, 0); } while (0)
; #define PG8_LDA(dst, b, h) do { _Pragma("unroll") for (int m = 0; m < 4; ++m) _Pragma("unroll") for (int k = 0; k < 2; ++k) dst[m][k] = *(const LAS bf16x8*)(lds + PG8_SA(b, h) + aoff + m * 2048 + k * 1024); } while (0)
; #define PG8_LDB(dst, b, h) do { _Pragma("unroll") for (int n = 0; n < 2; ++n) _Pragma("unroll") for (int k = 0; k < 2; ++k) dst[n][k] = *(const LAS bf16x8*)(lds + PG8_SB(b, h) + boff + n * 2048 + k * 1024); } while (0)
; #define PG8_MMA(ai, bj, At, Bt) do { __builtin_amdgcn_s_setprio(1); _Pragma("unroll") for (int m = 0; m < 4; ++m) _Pragma("unroll") for (int n = 0; n < 2; ++n) _Pragma("unroll") for (int k = 0; k < 2; ++k) \
;         acc[ai][bj][m][n] = __builtin_amdgcn_mfma_f32_16x16x32_bf16(Bt[n][k], At[m][k], acc[ai][bj][m][n], 0, 0, 0); __builtin_amdgcn_s_setprio(0); } while (0)
; #define PG8_WAIT_V(n) asm volatile("s_waitcnt vmcnt(" #n ")" ::: "memory")
; #define PG8_WAIT_L(n) asm volatile("s_waitcnt lgkmcnt(" #n ")" ::: "memory")
; #define PG8_BAR __builtin_amdgcn_s_barrier()
; #define PG8_SCHED __builtin_amdgcn_sched_barrier(0)
; template <class Epi, bool ALIGN_EPI = true, bool SP2 = true>
; __device__ __forceinline__ void gemm_phase(LAS unsigned char* lds, const Gemm g, const Order& S, const Epi& E) {
;     ...
;             PG8_LDB(B0, 1, 0); PG8_LDB(B1, 1, 1); PG8_SCHED; PG8_LDA(At, 1, 0); PG8_STAGE(PG8_SA(0, 1), a2 + hstepA, voffA);
;             PG8_WAIT_V(8); PG8_WAIT_L(0); PG8_BAR; PG8_MMA(0, 0, At, B0); PG8_MMA(0, 1, At, B1); PG8_BAR; PG8_SCHED;
	s_add_i32 s53, 0, 0x18000
	v_add_u32_e32 v0, s53, v185
	s_add_i32 s58, 0, 0x1c000
	ds_read_b128 v[130:133], v0
	ds_read_b128 v[134:137], v0 offset:1024
	ds_read_b128 v[138:141], v0 offset:2048
	ds_read_b128 v[142:145], v0 offset:3072
	v_add_u32_e32 v0, s58, v185
	ds_read_b128 v[146:149], v0
	ds_read_b128 v[150:153], v0 offset:1024
	ds_read_b128 v[154:157], v0 offset:2048
	ds_read_b128 v[158:161], v0 offset:3072
	s_add_u32 s54, vcc_lo, 0x40000
	s_addc_u32 s55, vcc_hi, 0
	s_mov_b32 m0, s35
	v_lshl_add_u64 v[242:243], s[54:55], 0, v[162:163]
	ds_read_b128 v[176:179], v189 offset:32768
	ds_read_b128 v[180:183], v189 offset:33792
	ds_read_b128 v[190:193], v189 offset:34816
	ds_read_b128 v[194:197], v189 offset:35840
	ds_read_b128 v[198:201], v189 offset:36864
	ds_read_b128 v[224:227], v189 offset:37888
	ds_read_b128 v[228:231], v189 offset:38912
	ds_read_b128 v[232:235], v189 offset:39936
	global_load_lds_dwordx4 v[242:243], off
	v_lshl_add_u64 v[242:243], s[54:55], 0, v[166:167]
	s_mov_b32 m0, s40
	s_nop 0
	global_load_lds_dwordx4 v[242:243], off
	s_waitcnt vmcnt(8)
	s_waitcnt lgkmcnt(0)
	s_barrier
	s_waitcnt lgkmcnt(0)
	v_mfma_f32_16x16x32_bf16 v[126:129], v[130:133], v[176:179], v[126:129]
	v_mfma_f32_16x16x32_bf16 v[122:125], v[138:141], v[176:179], v[122:125]
	v_mfma_f32_16x16x32_bf16 v[110:113], v[130:133], v[190:193], v[110:113]
	v_mfma_f32_16x16x32_bf16 v[106:109], v[138:141], v[190:193], v[106:109]
	v_mfma_f32_16x16x32_bf16 v[94:97], v[130:133], v[198:201], v[94:97]
	v_mfma_f32_16x16x32_bf16 v[90:93], v[138:141], v[198:201], v[90:93]
	v_mfma_f32_16x16x32_bf16 v[78:81], v[130:133], v[228:231], v[78:81]
	v_mfma_f32_16x16x32_bf16 v[74:77], v[138:141], v[228:231], v[74:77]
	v_mfma_f32_16x16x32_bf16 v[126:129], v[134:137], v[180:183], v[126:129]
	v_mfma_f32_16x16x32_bf16 v[122:125], v[142:145], v[180:183], v[122:125]
	v_mfma_f32_16x16x32_bf16 v[110:113], v[134:137], v[194:197], v[110:113]
	v_mfma_f32_16x16x32_bf16 v[106:109], v[142:145], v[194:197], v[106:109]
	v_mfma_f32_16x16x32_bf16 v[94:97], v[134:137], v[224:227], v[94:97]
	v_mfma_f32_16x16x32_bf16 v[90:93], v[142:145], v[224:227], v[90:93]
	v_mfma_f32_16x16x32_bf16 v[78:81], v[134:137], v[232:235], v[78:81]
	v_mfma_f32_16x16x32_bf16 v[74:77], v[142:145], v[232:235], v[74:77]
	v_mfma_f32_16x16x32_bf16 v[118:121], v[146:149], v[176:179], v[118:121]
	v_mfma_f32_16x16x32_bf16 v[114:117], v[154:157], v[176:179], v[114:117]
	v_mfma_f32_16x16x32_bf16 v[102:105], v[146:149], v[190:193], v[102:105]
	v_mfma_f32_16x16x32_bf16 v[98:101], v[154:157], v[190:193], v[98:101]
	v_mfma_f32_16x16x32_bf16 v[86:89], v[146:149], v[198:201], v[86:89]
	v_mfma_f32_16x16x32_bf16 v[82:85], v[154:157], v[198:201], v[82:85]
	v_mfma_f32_16x16x32_bf16 v[70:73], v[146:149], v[228:231], v[70:73]
	v_mfma_f32_16x16x32_bf16 v[66:69], v[154:157], v[228:231], v[66:69]
	v_mfma_f32_16x16x32_bf16 v[118:121], v[150:153], v[180:183], v[118:121]
	v_mfma_f32_16x16x32_bf16 v[114:117], v[158:161], v[180:183], v[114:117]
	v_mfma_f32_16x16x32_bf16 v[102:105], v[150:153], v[194:197], v[102:105]
	v_mfma_f32_16x16x32_bf16 v[98:101], v[158:161], v[194:197], v[98:101]
	v_mfma_f32_16x16x32_bf16 v[86:89], v[150:153], v[224:227], v[86:89]
	v_mfma_f32_16x16x32_bf16 v[82:85], v[158:161], v[224:227], v[82:85]
	v_mfma_f32_16x16x32_bf16 v[70:73], v[150:153], v[232:235], v[70:73]
	v_mfma_f32_16x16x32_bf16 v[66:69], v[158:161], v[232:235], v[66:69]
	s_barrier
; #define PG8_STAGE(bufoff, gbase, voff) do { _Pragma("unroll") for (int _i = 0; _i < 2; ++_i) \
;         __builtin_amdgcn_global_load_lds((const unsigned*)((const char*)(gbase) + (voff)[_i]), (LAS unsigned*)(lds + (bufoff) + ldsw + _i * 8192), 16, 0, 0); } while (0)
; #define PG8_LDA(dst, b, h) do { _Pragma("unroll") for (int m = 0; m < 4; ++m) _Pragma("unroll") for (int k = 0; k < 2; ++k) dst[m][k] = *(const LAS bf16x8*)(lds + PG8_SA(b, h) + aoff + m * 2048 + k * 1024); } while (0)
; #define PG8_MMA(ai, bj, At, Bt) do { __builtin_amdgcn_s_setprio(1); _Pragma("unroll") for (int m = 0; m < 4; ++m) _Pragma("unroll") for (int n = 0; n < 2; ++n) _Pragma("unroll") for (int k = 0; k < 2; ++k) \
;         acc[ai][bj][m][n] = __builtin_amdgcn_mfma_f32_16x16x32_bf16(Bt[n][k], At[m][k], acc[ai][bj][m][n], 0, 0, 0); __builtin_amdgcn_s_setprio(0); } while (0)
; #define PG8_WAIT_V(n) asm volatile("s_waitcnt vmcnt(" #n ")" ::: "memory")
; #define PG8_WAIT_L(n) asm volatile("s_waitcnt lgkmcnt(" #n ")" ::: "memory")
; #define PG8_BAR __builtin_amdgcn_s_barrier()
; #define PG8_SCHED __builtin_amdgcn_sched_barrier(0)
; template <class Epi, bool ALIGN_EPI = true, bool SP2 = true>
; __device__ __forceinline__ void gemm_phase(LAS unsigned char* lds, const Gemm g, const Order& S, const Epi& E) {
;     ...
;             PG8_LDA(At, 1, 1); PG8_STAGE(PG8_SB(1, 0), b3, voffB); PG8_STAGE(PG8_SB(1, 1), b3 + hstepB, voffB); PG8_STAGE(PG8_SA(1, 0), a3, voffA);
;             PG8_WAIT_V(8); PG8_WAIT_L(0); PG8_BAR; PG8_MMA(1, 0, At, B0); PG8_MMA(1, 1, At, B1); PG8_BAR; PG8_SCHED;
;     ...
;         if constexpr (ALIGN_EPI) { if (wr == 0) PG8_BAR; }
	s_add_i32 s53, s53, s21
	v_lshl_add_u64 v[202:203], v[202:203], 0, s[26:27]
	s_mov_b32 m0, s53
	ds_read_b128 v[176:179], v189 offset:49152
	ds_read_b128 v[180:183], v189 offset:50176
	ds_read_b128 v[190:193], v189 offset:51200
	ds_read_b128 v[194:197], v189 offset:52224
	ds_read_b128 v[198:201], v189 offset:53248
	ds_read_b128 v[224:227], v189 offset:54272
	ds_read_b128 v[228:231], v189 offset:55296
	ds_read_b128 v[232:235], v189 offset:56320
	global_load_lds_dwordx4 v[202:203], off
	s_add_i32 m0, s53, 0x2000
	s_add_u32 s14, s14, 0x40080
	v_lshl_add_u64 v[202:203], v[236:237], 0, s[26:27]
	s_addc_u32 s15, s15, 0
	s_add_i32 s53, s58, s21
	global_load_lds_dwordx4 v[202:203], off
	v_lshl_add_u64 v[202:203], s[14:15], 0, v[164:165]
	s_mov_b32 m0, s53
	s_nop 0
	global_load_lds_dwordx4 v[202:203], off
	v_lshl_add_u64 v[202:203], s[14:15], 0, v[168:169]
	s_add_i32 m0, s53, 0x2000
	s_nop 0
	global_load_lds_dwordx4 v[202:203], off
	v_lshl_add_u64 v[202:203], v[238:239], 0, s[26:27]
	s_mov_b32 m0, s44
	s_nop 0
	global_load_lds_dwordx4 v[202:203], off
	v_lshl_add_u64 v[202:203], v[240:241], 0, s[26:27]
	s_mov_b32 m0, s45
	s_nop 0
	global_load_lds_dwordx4 v[202:203], off
	s_waitcnt vmcnt(8)
	s_waitcnt lgkmcnt(0)
	s_barrier
	s_waitcnt lgkmcnt(0)
	v_mfma_f32_16x16x32_bf16 v[62:65], v[130:133], v[176:179], v[62:65]
	v_mfma_f32_16x16x32_bf16 v[58:61], v[138:141], v[176:179], v[58:61]
	v_mfma_f32_16x16x32_bf16 v[50:53], v[130:133], v[190:193], v[50:53]
	v_mfma_f32_16x16x32_bf16 v[42:45], v[138:141], v[190:193], v[42:45]
	v_mfma_f32_16x16x32_bf16 v[34:37], v[130:133], v[198:201], v[34:37]
	v_mfma_f32_16x16x32_bf16 v[26:29], v[138:141], v[198:201], v[26:29]
	v_mfma_f32_16x16x32_bf16 v[18:21], v[130:133], v[228:231], v[18:21]
	v_mfma_f32_16x16x32_bf16 v[10:13], v[138:141], v[228:231], v[10:13]
	v_mfma_f32_16x16x32_bf16 v[62:65], v[134:137], v[180:183], v[62:65]
	v_mfma_f32_16x16x32_bf16 v[58:61], v[142:145], v[180:183], v[58:61]
	v_mfma_f32_16x16x32_bf16 v[50:53], v[134:137], v[194:197], v[50:53]
	v_mfma_f32_16x16x32_bf16 v[42:45], v[142:145], v[194:197], v[42:45]
	v_mfma_f32_16x16x32_bf16 v[34:37], v[134:137], v[224:227], v[34:37]
	v_mfma_f32_16x16x32_bf16 v[26:29], v[142:145], v[224:227], v[26:29]
	v_mfma_f32_16x16x32_bf16 v[18:21], v[134:137], v[232:235], v[18:21]
	v_mfma_f32_16x16x32_bf16 v[10:13], v[142:145], v[232:235], v[10:13]
	v_mfma_f32_16x16x32_bf16 v[54:57], v[146:149], v[176:179], v[54:57]
	v_mfma_f32_16x16x32_bf16 v[46:49], v[154:157], v[176:179], v[46:49]
	v_mfma_f32_16x16x32_bf16 v[38:41], v[146:149], v[190:193], v[38:41]
	v_mfma_f32_16x16x32_bf16 v[30:33], v[154:157], v[190:193], v[30:33]
	v_mfma_f32_16x16x32_bf16 v[22:25], v[146:149], v[198:201], v[22:25]
	v_mfma_f32_16x16x32_bf16 v[14:17], v[154:157], v[198:201], v[14:17]
	v_mfma_f32_16x16x32_bf16 v[6:9], v[146:149], v[228:231], v[6:9]
	v_mfma_f32_16x16x32_bf16 v[2:5], v[154:157], v[228:231], v[2:5]
	v_mfma_f32_16x16x32_bf16 v[54:57], v[150:153], v[180:183], v[54:57]
	v_mfma_f32_16x16x32_bf16 v[46:49], v[158:161], v[180:183], v[46:49]
	v_mfma_f32_16x16x32_bf16 v[38:41], v[150:153], v[194:197], v[38:41]
	v_mfma_f32_16x16x32_bf16 v[30:33], v[158:161], v[194:197], v[30:33]
	v_mfma_f32_16x16x32_bf16 v[22:25], v[150:153], v[224:227], v[22:25]
	v_mfma_f32_16x16x32_bf16 v[14:17], v[158:161], v[224:227], v[14:17]
	v_mfma_f32_16x16x32_bf16 v[6:9], v[150:153], v[232:235], v[6:9]
	v_mfma_f32_16x16x32_bf16 v[2:5], v[158:161], v[232:235], v[2:5]
	s_barrier
	s_add_i32 s52, s52, 2
	s_add_u32 s12, s12, 0x100
	s_addc_u32 s13, s13, 0
	s_add_u32 s50, s50, 0x100
	s_addc_u32 s51, s51, 0
	s_cmp_gt_u32 s52, 13
	s_cbranch_scc0 .LBB0_161
	s_setprio 0
	s_and_b64 vcc, exec, s[80:81]
	s_cbranch_vccz .LBB0_164
	s_barrier

; template <class Epi, bool ALIGN_EPI = true, bool SP2 = true>
; __device__ __forceinline__ void gemm_phase(LAS unsigned char* lds, const Gemm g, const Order& S, const Epi& E) {
;     ...
;         const int nt = cur.nkt;
;         for (int t = 0; t < nt; t += 2) {
;             const bool last = (t == nt - 2);
;             const char* a1 = cA + (size_t)(t + 1) * kstep;
;             const char* a2 = last ? nA : cA + (size_t)(t + 2) * kstep; const char* b2 = last ? nB : cB + (size_t)(t + 2) * kstep;
.LBB0_509:
	s_add_i32 s5, s19, -2
	s_add_u32 s15, s68, 0x100
	s_addc_u32 s21, s69, 0
	s_mov_b32 s24, 0
	s_cmp_lg_u32 s12, 0
	s_cbranch_scc1 .Lsprio_skip_1
	s_setprio 1

; #define PG8_STAGE(bufoff, gbase, voff) do { _Pragma("unroll") for (int _i = 0; _i < 2; ++_i) \
;         __builtin_amdgcn_global_load_lds((const unsigned*)((const char*)(gbase) + (voff)[_i]), (LAS unsigned*)(lds + (bufoff) + ldsw + _i * 8192), 16, 0, 0); } while (0)
; #define PG8_LDA(dst, b, h) do { _Pragma("unroll") for (int m = 0; m < 4; ++m) _Pragma("unroll") for (int k = 0; k < 2; ++k) dst[m][k] = *(const LAS bf16x8*)(lds + PG8_SA(b, h) + aoff + m * 2048 + k * 1024); } while (0)
; #define PG8_LDB(dst, b, h) do { _Pragma("unroll") for (int n = 0; n < 2; ++n) _Pragma("unroll") for (int k = 0; k < 2; ++k) dst[n][k] = *(const LAS bf16x8*)(lds + PG8_SB(b, h) + boff + n * 2048 + k * 1024); } while (0)
; #define PG8_MMA(ai, bj, At, Bt) do { __builtin_amdgcn_s_setprio(1); _Pragma("unroll") for (int m = 0; m < 4; ++m) _Pragma("unroll") for (int n = 0; n < 2; ++n) _Pragma("unroll") for (int k = 0; k < 2; ++k) \
;         acc[ai][bj][m][n] = __builtin_amdgcn_mfma_f32_16x16x32_bf16(Bt[n][k], At[m][k], acc[ai][bj][m][n], 0, 0, 0); __builtin_amdgcn_s_setprio(0); } while (0)
; #define PG8_WAIT_V(n) asm volatile("s_waitcnt vmcnt(" #n ")" ::: "memory")
; #define PG8_WAIT_L(n) asm volatile("s_waitcnt lgkmcnt(" #n ")" ::: "memory")
; #define PG8_BAR __builtin_amdgcn_s_barrier()
; #define PG8_SCHED __builtin_amdgcn_sched_barrier(0)
; template <class Epi, bool ALIGN_EPI = true, bool SP2 = true>
; __device__ __forceinline__ void gemm_phase(LAS unsigned char* lds, const Gemm g, const Order& S, const Epi& E) {
;     ...
;             const bool last = (t == nt - 2);
;             const char* a1 = cA + (size_t)(t + 1) * kstep;
;             const char* a2 = last ? nA : cA + (size_t)(t + 2) * kstep; const char* b2 = last ? nB : cB + (size_t)(t + 2) * kstep;
;             const char* a3 = a2 + kstep; const char* b3 = b2 + kstep;
;             if constexpr (SP2) {
;             PG8_LDB(B0, 0, 0); PG8_LDB(B1, 0, 1); PG8_SCHED; PG8_LDA(At, 0, 0); PG8_STAGE(PG8_SA(1, 1), a1 + hstepA, voffA);
;             PG8_WAIT_V(8); PG8_WAIT_L(0); PG8_BAR; PG8_MMA(0, 0, At, B0); PG8_MMA(0, 1, At, B1); PG8_BAR; PG8_SCHED;
;             PG8_LDA(At, 0, 1); PG8_STAGE(PG8_SB(0, 0), b2, voffB); PG8_STAGE(PG8_SB(0, 1), b2 + hstepB, voffB); PG8_STAGE(PG8_SA(0, 0), a2, voffA);
;             PG8_WAIT_V(8); PG8_WAIT_L(0); PG8_BAR; PG8_MMA(1, 0, At, B0); PG8_MMA(1, 1, At, B1); PG8_BAR; PG8_SCHED;
.LBB0_510:
	s_add_i32 s23, s24, 2
	s_add_u32 s68, s64, 0x100
	s_addc_u32 s69, s65, 0
	s_add_i32 s25, 0, 0x10000
	s_cmp_eq_u32 s5, s24
	s_cselect_b32 s73, s61, s69
	s_cselect_b32 s72, s60, s68
	v_add_u32_e32 v0, s25, v178
	s_cselect_b32 s71, s63, s21
	s_cselect_b32 s70, s62, s15
	s_add_i32 s34, 0, 0x14000
	ds_read_b128 v[132:135], v0
	ds_read_b128 v[136:139], v0 offset:1024
	ds_read_b128 v[170:173], v0 offset:2048
	ds_read_b128 v[174:177], v0 offset:3072
	v_add_u32_e32 v0, s34, v178
	ds_read_b128 v[180:183], v0
	ds_read_b128 v[184:187], v0 offset:1024
	ds_read_b128 v[188:191], v0 offset:2048
	ds_read_b128 v[192:195], v0 offset:3072
	v_lshl_add_u64 v[2:3], s[64:65], 0, v[166:167]
	s_add_i32 m0, s67, 0xc000
	ds_read_b128 v[196:199], v179
	ds_read_b128 v[200:203], v179 offset:1024
	ds_read_b128 v[224:227], v179 offset:2048
	ds_read_b128 v[228:231], v179 offset:3072
	ds_read_b128 v[232:235], v179 offset:4096
	ds_read_b128 v[236:239], v179 offset:5120
	ds_read_b128 v[240:243], v179 offset:6144
	ds_read_b128 v[244:247], v179 offset:7168
	global_load_lds_dwordx4 v[2:3], off
	v_lshl_add_u64 v[2:3], s[64:65], 0, v[168:169]
	s_add_i32 m0, s67, 0xe000
	s_nop 0
	global_load_lds_dwordx4 v[2:3], off
	s_waitcnt vmcnt(8)
	s_waitcnt lgkmcnt(0)
	s_barrier
	s_waitcnt lgkmcnt(0)
	v_mfma_f32_16x16x32_bf16 v[128:131], v[132:135], v[196:199], v[128:131]
	v_mfma_f32_16x16x32_bf16 v[124:127], v[170:173], v[196:199], v[124:127]
	v_mfma_f32_16x16x32_bf16 v[120:123], v[132:135], v[224:227], v[120:123]
	v_mfma_f32_16x16x32_bf16 v[116:119], v[170:173], v[224:227], v[116:119]
	v_mfma_f32_16x16x32_bf16 v[112:115], v[132:135], v[232:235], v[112:115]
	v_mfma_f32_16x16x32_bf16 v[108:111], v[170:173], v[232:235], v[108:111]
	v_mfma_f32_16x16x32_bf16 v[104:107], v[132:135], v[240:243], v[104:107]
	v_mfma_f32_16x16x32_bf16 v[100:103], v[170:173], v[240:243], v[100:103]
	v_mfma_f32_16x16x32_bf16 v[128:131], v[136:139], v[200:203], v[128:131]
	v_mfma_f32_16x16x32_bf16 v[124:127], v[174:177], v[200:203], v[124:127]
	v_mfma_f32_16x16x32_bf16 v[120:123], v[136:139], v[228:231], v[120:123]
	v_mfma_f32_16x16x32_bf16 v[116:119], v[174:177], v[228:231], v[116:119]
	v_mfma_f32_16x16x32_bf16 v[112:115], v[136:139], v[236:239], v[112:115]
	v_mfma_f32_16x16x32_bf16 v[108:111], v[174:177], v[236:239], v[108:111]
	v_mfma_f32_16x16x32_bf16 v[104:107], v[136:139], v[244:247], v[104:107]
	v_mfma_f32_16x16x32_bf16 v[100:103], v[174:177], v[244:247], v[100:103]
	v_mfma_f32_16x16x32_bf16 v[96:99], v[180:183], v[196:199], v[96:99]
	v_mfma_f32_16x16x32_bf16 v[92:95], v[188:191], v[196:199], v[92:95]
	v_mfma_f32_16x16x32_bf16 v[88:91], v[180:183], v[224:227], v[88:91]
	v_mfma_f32_16x16x32_bf16 v[84:87], v[188:191], v[224:227], v[84:87]
	v_mfma_f32_16x16x32_bf16 v[80:83], v[180:183], v[232:235], v[80:83]
	v_mfma_f32_16x16x32_bf16 v[76:79], v[188:191], v[232:235], v[76:79]
	v_mfma_f32_16x16x32_bf16 v[72:75], v[180:183], v[240:243], v[72:75]
	v_mfma_f32_16x16x32_bf16 v[68:71], v[188:191], v[240:243], v[68:71]
	v_mfma_f32_16x16x32_bf16 v[96:99], v[184:187], v[200:203], v[96:99]
	v_mfma_f32_16x16x32_bf16 v[92:95], v[192:195], v[200:203], v[92:95]
	v_mfma_f32_16x16x32_bf16 v[88:91], v[184:187], v[228:231], v[88:91]
	v_mfma_f32_16x16x32_bf16 v[84:87], v[192:195], v[228:231], v[84:87]
	v_mfma_f32_16x16x32_bf16 v[80:83], v[184:187], v[236:239], v[80:83]
	v_mfma_f32_16x16x32_bf16 v[76:79], v[192:195], v[236:239], v[76:79]
	v_mfma_f32_16x16x32_bf16 v[72:75], v[184:187], v[244:247], v[72:75]
	v_mfma_f32_16x16x32_bf16 v[68:71], v[192:195], v[244:247], v[68:71]
	s_barrier
	s_add_i32 s24, s25, s76
	v_lshl_add_u64 v[248:249], s[70:71], 0, v[142:143]
	s_mov_b32 m0, s24
	ds_read_b128 v[196:199], v179 offset:16384
	ds_read_b128 v[200:203], v179 offset:17408
	ds_read_b128 v[224:227], v179 offset:18432
	ds_read_b128 v[228:231], v179 offset:19456
	ds_read_b128 v[232:235], v179 offset:20480
	ds_read_b128 v[236:239], v179 offset:21504
	ds_read_b128 v[240:243], v179 offset:22528
	ds_read_b128 v[244:247], v179 offset:23552
	global_load_lds_dwordx4 v[248:249], off
	s_add_i32 m0, s24, 0x2000
	s_add_u32 s24, s70, 0x40000
	v_lshl_add_u64 v[250:251], s[70:71], 0, v[146:147]
	s_addc_u32 s25, s71, 0
	s_add_i32 s34, s34, s76
	global_load_lds_dwordx4 v[250:251], off
	v_lshl_add_u64 v[2:3], s[24:25], 0, v[142:143]
	s_mov_b32 m0, s34
	v_lshl_add_u64 v[252:253], s[72:73], 0, v[140:141]
	global_load_lds_dwordx4 v[2:3], off
	v_lshl_add_u64 v[2:3], s[24:25], 0, v[146:147]
	s_add_i32 m0, s34, 0x2000
	v_lshl_add_u64 v[210:211], s[72:73], 0, v[144:145]
	global_load_lds_dwordx4 v[2:3], off
	s_mov_b32 m0, s67
	s_nop 0
	global_load_lds_dwordx4 v[252:253], off
	s_mov_b32 m0, s83
	s_nop 0
	global_load_lds_dwordx4 v[210:211], off
	s_waitcnt vmcnt(8)
	s_waitcnt lgkmcnt(0)
	s_barrier
; #define PG8_STAGE(bufoff, gbase, voff) do { _Pragma("unroll") for (int _i = 0; _i < 2; ++_i) \
;         __builtin_amdgcn_global_load_lds((const unsigned*)((const char*)(gbase) + (voff)[_i]), (LAS unsigned*)(lds + (bufoff) + ldsw + _i * 8192), 16, 0, 0); } while (0)
; #define PG8_LDA(dst, b, h) do { _Pragma("unroll") for (int m = 0; m < 4; ++m) _Pragma("unroll") for (int k = 0; k < 2; ++k) dst[m][k] = *(const LAS bf16x8*)(lds + PG8_SA(b, h) + aoff + m * 2048 + k * 1024); } while (0)
; #define PG8_LDB(dst, b, h) do { _Pragma("unroll") for (int n = 0; n < 2; ++n) _Pragma("unroll") for (int k = 0; k < 2; ++k) dst[n][k] = *(const LAS bf16x8*)(lds + PG8_SB(b, h) + boff + n * 2048 + k * 1024); } while (0)
; #define PG8_MMA(ai, bj, At, Bt) do { __builtin_amdgcn_s_setprio(1); _Pragma("unroll") for (int m = 0; m < 4; ++m) _Pragma("unroll") for (int n = 0; n < 2; ++n) _Pragma("unroll") for (int k = 0; k < 2; ++k) \
;         acc[ai][bj][m][n] = __builtin_amdgcn_mfma_f32_16x16x32_bf16(Bt[n][k], At[m][k], acc[ai][bj][m][n], 0, 0, 0); __builtin_amdgcn_s_setprio(0); } while (0)
; #define PG8_WAIT_V(n) asm volatile("s_waitcnt vmcnt(" #n ")" ::: "memory")
; #define PG8_WAIT_L(n) asm volatile("s_waitcnt lgkmcnt(" #n ")" ::: "memory")
; #define PG8_BAR __builtin_amdgcn_s_barrier()
; #define PG8_SCHED __builtin_amdgcn_sched_barrier(0)
; template <class Epi, bool ALIGN_EPI = true, bool SP2 = true>
; __device__ __forceinline__ void gemm_phase(LAS unsigned char* lds, const Gemm g, const Order& S, const Epi& E) {
;     ...
;             PG8_WAIT_V(8); PG8_WAIT_L(0); PG8_BAR; PG8_MMA(1, 0, At, B0); PG8_MMA(1, 1, At, B1); PG8_BAR; PG8_SCHED;
;             PG8_LDB(B0, 1, 0); PG8_LDB(B1, 1, 1); PG8_SCHED; PG8_LDA(At, 1, 0); PG8_STAGE(PG8_SA(0, 1), a2 + hstepA, voffA);
;             PG8_WAIT_V(8); PG8_WAIT_L(0); PG8_BAR; PG8_MMA(0, 0, At, B0); PG8_MMA(0, 1, At, B1); PG8_BAR; PG8_SCHED;
	s_waitcnt lgkmcnt(0)
	v_mfma_f32_16x16x32_bf16 v[64:67], v[132:135], v[196:199], v[64:67]
	v_mfma_f32_16x16x32_bf16 v[60:63], v[170:173], v[196:199], v[60:63]
	v_mfma_f32_16x16x32_bf16 v[56:59], v[132:135], v[224:227], v[56:59]
	v_mfma_f32_16x16x32_bf16 v[52:55], v[170:173], v[224:227], v[52:55]
	v_mfma_f32_16x16x32_bf16 v[48:51], v[132:135], v[232:235], v[48:51]
	v_mfma_f32_16x16x32_bf16 v[44:47], v[170:173], v[232:235], v[44:47]
	v_mfma_f32_16x16x32_bf16 v[40:43], v[132:135], v[240:243], v[40:43]
	v_mfma_f32_16x16x32_bf16 v[36:39], v[170:173], v[240:243], v[36:39]
	v_mfma_f32_16x16x32_bf16 v[64:67], v[136:139], v[200:203], v[64:67]
	v_mfma_f32_16x16x32_bf16 v[60:63], v[174:177], v[200:203], v[60:63]
	v_mfma_f32_16x16x32_bf16 v[56:59], v[136:139], v[228:231], v[56:59]
	v_mfma_f32_16x16x32_bf16 v[52:55], v[174:177], v[228:231], v[52:55]
	v_mfma_f32_16x16x32_bf16 v[48:51], v[136:139], v[236:239], v[48:51]
	v_mfma_f32_16x16x32_bf16 v[44:47], v[174:177], v[236:239], v[44:47]
	v_mfma_f32_16x16x32_bf16 v[40:43], v[136:139], v[244:247], v[40:43]
	v_mfma_f32_16x16x32_bf16 v[36:39], v[174:177], v[244:247], v[36:39]
	v_mfma_f32_16x16x32_bf16 v[32:35], v[180:183], v[196:199], v[32:35]
	v_mfma_f32_16x16x32_bf16 v[28:31], v[188:191], v[196:199], v[28:31]
	v_mfma_f32_16x16x32_bf16 v[24:27], v[180:183], v[224:227], v[24:27]
	v_mfma_f32_16x16x32_bf16 v[20:23], v[188:191], v[224:227], v[20:23]
	v_mfma_f32_16x16x32_bf16 v[16:19], v[180:183], v[232:235], v[16:19]
	v_mfma_f32_16x16x32_bf16 v[12:15], v[188:191], v[232:235], v[12:15]
	v_mfma_f32_16x16x32_bf16 v[8:11], v[180:183], v[240:243], v[8:11]
	v_mfma_f32_16x16x32_bf16 v[2:5], v[188:191], v[240:243], v[4:7]
	v_mfma_f32_16x16x32_bf16 v[32:35], v[184:187], v[200:203], v[32:35]
	v_mfma_f32_16x16x32_bf16 v[28:31], v[192:195], v[200:203], v[28:31]
	v_mfma_f32_16x16x32_bf16 v[24:27], v[184:187], v[228:231], v[24:27]
	v_mfma_f32_16x16x32_bf16 v[20:23], v[192:195], v[228:231], v[20:23]
	v_mfma_f32_16x16x32_bf16 v[16:19], v[184:187], v[236:239], v[16:19]
	v_mfma_f32_16x16x32_bf16 v[12:15], v[192:195], v[236:239], v[12:15]
	v_mfma_f32_16x16x32_bf16 v[8:11], v[184:187], v[244:247], v[8:11]
	v_mfma_f32_16x16x32_bf16 v[2:5], v[192:195], v[244:247], v[2:5]
	s_barrier
	s_add_i32 s34, 0, 0x18000
	v_add_u32_e32 v0, s34, v178
	s_add_i32 s35, 0, 0x1c000
	ds_read_b128 v[132:135], v0
	ds_read_b128 v[136:139], v0 offset:1024
	ds_read_b128 v[170:173], v0 offset:2048
	ds_read_b128 v[174:177], v0 offset:3072
	v_add_u32_e32 v0, s35, v178
	ds_read_b128 v[180:183], v0
	ds_read_b128 v[184:187], v0 offset:1024
	ds_read_b128 v[188:191], v0 offset:2048
	ds_read_b128 v[192:195], v0 offset:3072
	s_add_u32 s24, s72, 0x140000
	s_addc_u32 s25, s73, 0
	s_mov_b32 m0, s84
	v_lshl_add_u64 v[6:7], s[24:25], 0, v[140:141]
	ds_read_b128 v[196:199], v179 offset:32768
	ds_read_b128 v[200:203], v179 offset:33792
	ds_read_b128 v[224:227], v179 offset:34816
	ds_read_b128 v[228:231], v179 offset:35840
	ds_read_b128 v[232:235], v179 offset:36864
	ds_read_b128 v[236:239], v179 offset:37888
	ds_read_b128 v[240:243], v179 offset:38912
	ds_read_b128 v[244:247], v179 offset:39936
	global_load_lds_dwordx4 v[6:7], off
	v_lshl_add_u64 v[6:7], s[24:25], 0, v[144:145]
	s_mov_b32 m0, s85
	s_nop 0
	global_load_lds_dwordx4 v[6:7], off
	s_waitcnt vmcnt(8)
	s_waitcnt lgkmcnt(0)
	s_barrier
	s_waitcnt lgkmcnt(0)
	v_mfma_f32_16x16x32_bf16 v[128:131], v[132:135], v[196:199], v[128:131]
	v_mfma_f32_16x16x32_bf16 v[124:127], v[170:173], v[196:199], v[124:127]
	v_mfma_f32_16x16x32_bf16 v[120:123], v[132:135], v[224:227], v[120:123]
	v_mfma_f32_16x16x32_bf16 v[116:119], v[170:173], v[224:227], v[116:119]
	v_mfma_f32_16x16x32_bf16 v[112:115], v[132:135], v[232:235], v[112:115]
	v_mfma_f32_16x16x32_bf16 v[108:111], v[170:173], v[232:235], v[108:111]
	v_mfma_f32_16x16x32_bf16 v[104:107], v[132:135], v[240:243], v[104:107]
	v_mfma_f32_16x16x32_bf16 v[100:103], v[170:173], v[240:243], v[100:103]
	v_mfma_f32_16x16x32_bf16 v[128:131], v[136:139], v[200:203], v[128:131]
	v_mfma_f32_16x16x32_bf16 v[124:127], v[174:177], v[200:203], v[124:127]
	v_mfma_f32_16x16x32_bf16 v[120:123], v[136:139], v[228:231], v[120:123]
	v_mfma_f32_16x16x32_bf16 v[116:119], v[174:177], v[228:231], v[116:119]
	v_mfma_f32_16x16x32_bf16 v[112:115], v[136:139], v[236:239], v[112:115]
	v_mfma_f32_16x16x32_bf16 v[108:111], v[174:177], v[236:239], v[108:111]
	v_mfma_f32_16x16x32_bf16 v[104:107], v[136:139], v[244:247], v[104:107]
	v_mfma_f32_16x16x32_bf16 v[100:103], v[174:177], v[244:247], v[100:103]
	v_mfma_f32_16x16x32_bf16 v[96:99], v[180:183], v[196:199], v[96:99]
	v_mfma_f32_16x16x32_bf16 v[92:95], v[188:191], v[196:199], v[92:95]
	v_mfma_f32_16x16x32_bf16 v[88:91], v[180:183], v[224:227], v[88:91]
	v_mfma_f32_16x16x32_bf16 v[84:87], v[188:191], v[224:227], v[84:87]
	v_mfma_f32_16x16x32_bf16 v[80:83], v[180:183], v[232:235], v[80:83]
	v_mfma_f32_16x16x32_bf16 v[76:79], v[188:191], v[232:235], v[76:79]
	v_mfma_f32_16x16x32_bf16 v[72:75], v[180:183], v[240:243], v[72:75]
	v_mfma_f32_16x16x32_bf16 v[68:71], v[188:191], v[240:243], v[68:71]
	v_mfma_f32_16x16x32_bf16 v[96:99], v[184:187], v[200:203], v[96:99]
	v_mfma_f32_16x16x32_bf16 v[92:95], v[192:195], v[200:203], v[92:95]
	v_mfma_f32_16x16x32_bf16 v[88:91], v[184:187], v[228:231], v[88:91]
	v_mfma_f32_16x16x32_bf16 v[84:87], v[192:195], v[228:231], v[84:87]
	v_mfma_f32_16x16x32_bf16 v[80:83], v[184:187], v[236:239], v[80:83]
	v_mfma_f32_16x16x32_bf16 v[76:79], v[192:195], v[236:239], v[76:79]
	v_mfma_f32_16x16x32_bf16 v[72:75], v[184:187], v[244:247], v[72:75]
	v_mfma_f32_16x16x32_bf16 v[68:71], v[192:195], v[244:247], v[68:71]
	s_barrier
; #define PG8_STAGE(bufoff, gbase, voff) do { _Pragma("unroll") for (int _i = 0; _i < 2; ++_i) \
;         __builtin_amdgcn_global_load_lds((const unsigned*)((const char*)(gbase) + (voff)[_i]), (LAS unsigned*)(lds + (bufoff) + ldsw + _i * 8192), 16, 0, 0); } while (0)
; #define PG8_LDA(dst, b, h) do { _Pragma("unroll") for (int m = 0; m < 4; ++m) _Pragma("unroll") for (int k = 0; k < 2; ++k) dst[m][k] = *(const LAS bf16x8*)(lds + PG8_SA(b, h) + aoff + m * 2048 + k * 1024); } while (0)
; #define PG8_MMA(ai, bj, At, Bt) do { __builtin_amdgcn_s_setprio(1); _Pragma("unroll") for (int m = 0; m < 4; ++m) _Pragma("unroll") for (int n = 0; n < 2; ++n) _Pragma("unroll") for (int k = 0; k < 2; ++k) \
;         acc[ai][bj][m][n] = __builtin_amdgcn_mfma_f32_16x16x32_bf16(Bt[n][k], At[m][k], acc[ai][bj][m][n], 0, 0, 0); __builtin_amdgcn_s_setprio(0); } while (0)
; #define PG8_WAIT_V(n) asm volatile("s_waitcnt vmcnt(" #n ")" ::: "memory")
; #define PG8_WAIT_L(n) asm volatile("s_waitcnt lgkmcnt(" #n ")" ::: "memory")
; #define PG8_BAR __builtin_amdgcn_s_barrier()
; #define PG8_SCHED __builtin_amdgcn_sched_barrier(0)
; template <class Epi, bool ALIGN_EPI = true, bool SP2 = true>
; __device__ __forceinline__ void gemm_phase(LAS unsigned char* lds, const Gemm g, const Order& S, const Epi& E) {
;     ...
;             PG8_LDA(At, 1, 1); PG8_STAGE(PG8_SB(1, 0), b3, voffB); PG8_STAGE(PG8_SB(1, 1), b3 + hstepB, voffB); PG8_STAGE(PG8_SA(1, 0), a3, voffA);
;             PG8_WAIT_V(8); PG8_WAIT_L(0); PG8_BAR; PG8_MMA(1, 0, At, B0); PG8_MMA(1, 1, At, B1); PG8_BAR; PG8_SCHED;
	s_add_i32 s24, s34, s76
	v_lshl_add_u64 v[6:7], v[248:249], 0, s[26:27]
	s_mov_b32 m0, s24
	ds_read_b128 v[196:199], v179 offset:49152
	ds_read_b128 v[200:203], v179 offset:50176
	ds_read_b128 v[224:227], v179 offset:51200
	ds_read_b128 v[228:231], v179 offset:52224
	ds_read_b128 v[232:235], v179 offset:53248
	ds_read_b128 v[236:239], v179 offset:54272
	ds_read_b128 v[240:243], v179 offset:55296
	ds_read_b128 v[244:247], v179 offset:56320
	global_load_lds_dwordx4 v[6:7], off
	s_add_i32 m0, s24, 0x2000
	s_add_u32 s24, s70, 0x40080
	v_lshl_add_u64 v[6:7], v[250:251], 0, s[26:27]
	s_addc_u32 s25, s71, 0
	s_add_i32 s34, s35, s76
	global_load_lds_dwordx4 v[6:7], off
	v_lshl_add_u64 v[6:7], s[24:25], 0, v[142:143]
	s_mov_b32 m0, s34
	s_nop 0
	global_load_lds_dwordx4 v[6:7], off
	v_lshl_add_u64 v[6:7], s[24:25], 0, v[146:147]
	s_add_i32 m0, s34, 0x2000
	s_nop 0
	global_load_lds_dwordx4 v[6:7], off
	v_lshl_add_u64 v[6:7], v[252:253], 0, s[26:27]
	s_mov_b32 m0, s88
	s_nop 0
	global_load_lds_dwordx4 v[6:7], off
	v_lshl_add_u64 v[6:7], v[210:211], 0, s[26:27]
	s_mov_b32 m0, s89
	s_nop 0
	global_load_lds_dwordx4 v[6:7], off
	s_waitcnt vmcnt(8)
	s_waitcnt lgkmcnt(0)
	s_barrier
	s_waitcnt lgkmcnt(0)
	v_mfma_f32_16x16x32_bf16 v[64:67], v[132:135], v[196:199], v[64:67]
	v_mfma_f32_16x16x32_bf16 v[60:63], v[170:173], v[196:199], v[60:63]
	v_mfma_f32_16x16x32_bf16 v[56:59], v[132:135], v[224:227], v[56:59]
	v_mfma_f32_16x16x32_bf16 v[52:55], v[170:173], v[224:227], v[52:55]
	v_mfma_f32_16x16x32_bf16 v[48:51], v[132:135], v[232:235], v[48:51]
	v_mfma_f32_16x16x32_bf16 v[44:47], v[170:173], v[232:235], v[44:47]
	v_mfma_f32_16x16x32_bf16 v[40:43], v[132:135], v[240:243], v[40:43]
	v_mfma_f32_16x16x32_bf16 v[36:39], v[170:173], v[240:243], v[36:39]
	v_mfma_f32_16x16x32_bf16 v[64:67], v[136:139], v[200:203], v[64:67]
	v_mfma_f32_16x16x32_bf16 v[60:63], v[174:177], v[200:203], v[60:63]
	v_mfma_f32_16x16x32_bf16 v[56:59], v[136:139], v[228:231], v[56:59]
	v_mfma_f32_16x16x32_bf16 v[52:55], v[174:177], v[228:231], v[52:55]
	v_mfma_f32_16x16x32_bf16 v[48:51], v[136:139], v[236:239], v[48:51]
	v_mfma_f32_16x16x32_bf16 v[44:47], v[174:177], v[236:239], v[44:47]
	v_mfma_f32_16x16x32_bf16 v[40:43], v[136:139], v[244:247], v[40:43]
	v_mfma_f32_16x16x32_bf16 v[36:39], v[174:177], v[244:247], v[36:39]
	v_mfma_f32_16x16x32_bf16 v[32:35], v[180:183], v[196:199], v[32:35]
	v_mfma_f32_16x16x32_bf16 v[28:31], v[188:191], v[196:199], v[28:31]
	v_mfma_f32_16x16x32_bf16 v[24:27], v[180:183], v[224:227], v[24:27]
	v_mfma_f32_16x16x32_bf16 v[20:23], v[188:191], v[224:227], v[20:23]
	v_mfma_f32_16x16x32_bf16 v[16:19], v[180:183], v[232:235], v[16:19]
	v_mfma_f32_16x16x32_bf16 v[12:15], v[188:191], v[232:235], v[12:15]
	v_mfma_f32_16x16x32_bf16 v[6:9], v[180:183], v[240:243], v[8:11]
	v_mfma_f32_16x16x32_bf16 v[2:5], v[188:191], v[240:243], v[2:5]
	v_mfma_f32_16x16x32_bf16 v[32:35], v[184:187], v[200:203], v[32:35]
	v_mfma_f32_16x16x32_bf16 v[28:31], v[192:195], v[200:203], v[28:31]
	v_mfma_f32_16x16x32_bf16 v[24:27], v[184:187], v[228:231], v[24:27]
	v_mfma_f32_16x16x32_bf16 v[20:23], v[192:195], v[228:231], v[20:23]
	v_mfma_f32_16x16x32_bf16 v[16:19], v[184:187], v[236:239], v[16:19]
	v_mfma_f32_16x16x32_bf16 v[12:15], v[192:195], v[236:239], v[12:15]
	v_mfma_f32_16x16x32_bf16 v[8:11], v[184:187], v[244:247], v[6:9]
	v_mfma_f32_16x16x32_bf16 v[4:7], v[192:195], v[244:247], v[2:5]
	s_barrier
	s_add_u32 s15, s15, 0x100
	s_addc_u32 s21, s21, 0
	s_cmp_ge_i32 s23, s19
	s_mov_b64 s[64:65], s[68:69]
	s_mov_b32 s24, s23
	s_cbranch_scc0 .LBB0_510
	s_setprio 0

; template <class Epi, bool ALIGN_EPI = true, bool SP2 = true>
; __device__ __forceinline__ void gemm_phase(LAS unsigned char* lds, const Gemm g, const Order& S, const Epi& E) {
;     ...
;         const int nt = cur.nkt;
;         for (int t = 0; t < nt; t += 2) {
;             const bool last = (t == nt - 2);
;             const char* a1 = cA + (size_t)(t + 1) * kstep;
;             const char* a2 = last ? nA : cA + (size_t)(t + 2) * kstep; const char* b2 = last ? nB : cB + (size_t)(t + 2) * kstep;
;     ...
;         for (int a = 0; a < 2; ++a)
; #pragma unroll
;             for (int b = 0; b < 2; ++b)
; #pragma unroll
;                 for (int m = 0; m < 4; ++m)
; #pragma unroll
;                     for (int n = 0; n < 2; ++n) acc[a][b][m][n] = (f32x4){0.f, 0.f, 0.f, 0.f};
.LBB0_723:
	s_add_i32 s13, s54, -2
	s_add_u32 s15, s68, 0x100
	v_mov_b32_e32 v2, 0
	s_addc_u32 s55, s69, 0
	s_mov_b32 s57, 0
	v_mov_b32_e32 v3, v2
	v_mov_b32_e32 v4, v2
	v_mov_b32_e32 v5, v2
	v_mov_b32_e32 v6, v2
	v_mov_b32_e32 v7, v2
	v_mov_b32_e32 v8, v2
	v_mov_b32_e32 v9, v2
	v_mov_b32_e32 v18, v2
	v_mov_b32_e32 v19, v2
	v_mov_b32_e32 v20, v2
	v_mov_b32_e32 v21, v2
	v_mov_b32_e32 v22, v2
	v_mov_b32_e32 v23, v2
	v_mov_b32_e32 v24, v2
	v_mov_b32_e32 v25, v2
	v_mov_b32_e32 v34, v2
	v_mov_b32_e32 v35, v2
	v_mov_b32_e32 v36, v2
	v_mov_b32_e32 v37, v2
	v_mov_b32_e32 v38, v2
	v_mov_b32_e32 v39, v2
	v_mov_b32_e32 v40, v2
	v_mov_b32_e32 v41, v2
	v_mov_b32_e32 v50, v2
	v_mov_b32_e32 v51, v2
	v_mov_b32_e32 v52, v2
	v_mov_b32_e32 v53, v2
	v_mov_b32_e32 v54, v2
	v_mov_b32_e32 v55, v2
	v_mov_b32_e32 v56, v2
	v_mov_b32_e32 v57, v2
	v_mov_b32_e32 v10, v2
	v_mov_b32_e32 v11, v2
	v_mov_b32_e32 v12, v2
	v_mov_b32_e32 v13, v2
	v_mov_b32_e32 v14, v2
	v_mov_b32_e32 v15, v2
	v_mov_b32_e32 v16, v2
	v_mov_b32_e32 v17, v2
	v_mov_b32_e32 v26, v2
	v_mov_b32_e32 v27, v2
	v_mov_b32_e32 v28, v2
	v_mov_b32_e32 v29, v2
	v_mov_b32_e32 v30, v2
	v_mov_b32_e32 v31, v2
	v_mov_b32_e32 v32, v2
	v_mov_b32_e32 v33, v2
	v_mov_b32_e32 v42, v2
	v_mov_b32_e32 v43, v2
	v_mov_b32_e32 v44, v2
	v_mov_b32_e32 v45, v2
	v_mov_b32_e32 v46, v2
	v_mov_b32_e32 v47, v2
	v_mov_b32_e32 v48, v2
	v_mov_b32_e32 v49, v2
	v_mov_b32_e32 v58, v2
	v_mov_b32_e32 v59, v2
	v_mov_b32_e32 v60, v2
	v_mov_b32_e32 v61, v2
	v_mov_b32_e32 v62, v2
	v_mov_b32_e32 v63, v2
	v_mov_b32_e32 v64, v2
	v_mov_b32_e32 v65, v2
	v_mov_b32_e32 v66, v2
	v_mov_b32_e32 v67, v2
	v_mov_b32_e32 v68, v2
	v_mov_b32_e32 v69, v2
	v_mov_b32_e32 v70, v2
	v_mov_b32_e32 v71, v2
	v_mov_b32_e32 v72, v2
	v_mov_b32_e32 v73, v2
	v_mov_b32_e32 v82, v2
	v_mov_b32_e32 v83, v2
	v_mov_b32_e32 v84, v2
	v_mov_b32_e32 v85, v2
	v_mov_b32_e32 v86, v2
	v_mov_b32_e32 v87, v2
	v_mov_b32_e32 v88, v2
	v_mov_b32_e32 v89, v2
	v_mov_b32_e32 v98, v2
	v_mov_b32_e32 v99, v2
	v_mov_b32_e32 v100, v2
	v_mov_b32_e32 v101, v2
	v_mov_b32_e32 v102, v2
	v_mov_b32_e32 v103, v2
	v_mov_b32_e32 v104, v2
	v_mov_b32_e32 v105, v2
	v_mov_b32_e32 v114, v2
	v_mov_b32_e32 v115, v2
	v_mov_b32_e32 v116, v2
	v_mov_b32_e32 v117, v2
	v_mov_b32_e32 v118, v2
	v_mov_b32_e32 v119, v2
	v_mov_b32_e32 v120, v2
	v_mov_b32_e32 v121, v2
	v_mov_b32_e32 v74, v2
	v_mov_b32_e32 v75, v2
	v_mov_b32_e32 v76, v2
	v_mov_b32_e32 v77, v2
	v_mov_b32_e32 v78, v2
	v_mov_b32_e32 v79, v2
	v_mov_b32_e32 v80, v2
	v_mov_b32_e32 v81, v2
	v_mov_b32_e32 v90, v2
	v_mov_b32_e32 v91, v2
	v_mov_b32_e32 v92, v2
	v_mov_b32_e32 v93, v2
	v_mov_b32_e32 v94, v2
	v_mov_b32_e32 v95, v2
	v_mov_b32_e32 v96, v2
	v_mov_b32_e32 v97, v2
	v_mov_b32_e32 v106, v2
	v_mov_b32_e32 v107, v2
	v_mov_b32_e32 v108, v2
	v_mov_b32_e32 v109, v2
	v_mov_b32_e32 v110, v2
	v_mov_b32_e32 v111, v2
	v_mov_b32_e32 v112, v2
	v_mov_b32_e32 v113, v2
	v_mov_b32_e32 v122, v2
	v_mov_b32_e32 v123, v2
	v_mov_b32_e32 v124, v2
	v_mov_b32_e32 v125, v2
	v_mov_b32_e32 v126, v2
	v_mov_b32_e32 v127, v2
	v_mov_b32_e32 v128, v2
	v_mov_b32_e32 v129, v2
	s_cmp_lg_u32 s10, 0
	s_cbranch_scc1 .Lsprio_skip_2
	s_setprio 1

; #define PG8_STAGE(bufoff, gbase, voff) do { _Pragma("unroll") for (int _i = 0; _i < 2; ++_i) \
;         __builtin_amdgcn_global_load_lds((const unsigned*)((const char*)(gbase) + (voff)[_i]), (LAS unsigned*)(lds + (bufoff) + ldsw + _i * 8192), 16, 0, 0); } while (0)
; #define PG8_LDA(dst, b, h) do { _Pragma("unroll") for (int m = 0; m < 4; ++m) _Pragma("unroll") for (int k = 0; k < 2; ++k) dst[m][k] = *(const LAS bf16x8*)(lds + PG8_SA(b, h) + aoff + m * 2048 + k * 1024); } while (0)
; #define PG8_LDB(dst, b, h) do { _Pragma("unroll") for (int n = 0; n < 2; ++n) _Pragma("unroll") for (int k = 0; k < 2; ++k) dst[n][k] = *(const LAS bf16x8*)(lds + PG8_SB(b, h) + boff + n * 2048 + k * 1024); } while (0)
; #define PG8_MMA(ai, bj, At, Bt) do { __builtin_amdgcn_s_setprio(1); _Pragma("unroll") for (int m = 0; m < 4; ++m) _Pragma("unroll") for (int n = 0; n < 2; ++n) _Pragma("unroll") for (int k = 0; k < 2; ++k) \
;         acc[ai][bj][m][n] = __builtin_amdgcn_mfma_f32_16x16x32_bf16(Bt[n][k], At[m][k], acc[ai][bj][m][n], 0, 0, 0); __builtin_amdgcn_s_setprio(0); } while (0)
; #define PG8_WAIT_V(n) asm volatile("s_waitcnt vmcnt(" #n ")" ::: "memory")
; #define PG8_WAIT_L(n) asm volatile("s_waitcnt lgkmcnt(" #n ")" ::: "memory")
; #define PG8_BAR __builtin_amdgcn_s_barrier()
; #define PG8_SCHED __builtin_amdgcn_sched_barrier(0)
; template <class Epi, bool ALIGN_EPI = true, bool SP2 = true>
; __device__ __forceinline__ void gemm_phase(LAS unsigned char* lds, const Gemm g, const Order& S, const Epi& E) {
;     ...
;             const bool last = (t == nt - 2);
;             const char* a1 = cA + (size_t)(t + 1) * kstep;
;             const char* a2 = last ? nA : cA + (size_t)(t + 2) * kstep; const char* b2 = last ? nB : cB + (size_t)(t + 2) * kstep;
;             const char* a3 = a2 + kstep; const char* b3 = b2 + kstep;
;             if constexpr (SP2) {
;             PG8_LDB(B0, 0, 0); PG8_LDB(B1, 0, 1); PG8_SCHED; PG8_LDA(At, 0, 0); PG8_STAGE(PG8_SA(1, 1), a1 + hstepA, voffA);
;             PG8_WAIT_V(8); PG8_WAIT_L(0); PG8_BAR; PG8_MMA(0, 0, At, B0); PG8_MMA(0, 1, At, B1); PG8_BAR; PG8_SCHED;
;             PG8_LDA(At, 0, 1); PG8_STAGE(PG8_SB(0, 0), b2, voffB); PG8_STAGE(PG8_SB(0, 1), b2 + hstepB, voffB); PG8_STAGE(PG8_SA(0, 0), a2, voffA);
;             PG8_WAIT_V(8); PG8_WAIT_L(0); PG8_BAR; PG8_MMA(1, 0, At, B0); PG8_MMA(1, 1, At, B1); PG8_BAR; PG8_SCHED;
.LBB0_724:
	s_add_i32 s63, s57, 2
	s_add_u32 s68, s66, 0x100
	s_addc_u32 s69, s67, 0
	s_add_i32 s65, 0, 0x10000
	s_cmp_eq_u32 s13, s57
	s_cselect_b32 s73, s59, s69
	s_cselect_b32 s72, s58, s68
	v_add_u32_e32 v158, s65, v160
	s_cselect_b32 s71, s61, s55
	s_cselect_b32 s70, s60, s15
	s_add_i32 s57, 0, 0x14000
	ds_read_b128 v[162:165], v158
	ds_read_b128 v[166:169], v158 offset:1024
	ds_read_b128 v[170:173], v158 offset:2048
	ds_read_b128 v[174:177], v158 offset:3072
	v_add_u32_e32 v158, s57, v160
	ds_read_b128 v[178:181], v158
	ds_read_b128 v[182:185], v158 offset:1024
	ds_read_b128 v[186:189], v158 offset:2048
	ds_read_b128 v[190:193], v158 offset:3072
	v_lshl_add_u64 v[158:159], s[66:67], 0, v[154:155]
	s_add_i32 m0, s35, 0xc000
	ds_read_b128 v[194:197], v161
	ds_read_b128 v[198:201], v161 offset:1024
	ds_read_b128 v[224:227], v161 offset:2048
	ds_read_b128 v[228:231], v161 offset:3072
	ds_read_b128 v[232:235], v161 offset:4096
	ds_read_b128 v[236:239], v161 offset:5120
	ds_read_b128 v[240:243], v161 offset:6144
	ds_read_b128 v[244:247], v161 offset:7168
	global_load_lds_dwordx4 v[158:159], off
	v_lshl_add_u64 v[158:159], s[66:67], 0, v[156:157]
	s_add_i32 m0, s35, 0xe000
	s_nop 0
	global_load_lds_dwordx4 v[158:159], off
	s_waitcnt vmcnt(8)
	s_waitcnt lgkmcnt(0)
	s_barrier
	s_waitcnt lgkmcnt(0)
	v_mfma_f32_16x16x32_bf16 v[126:129], v[162:165], v[194:197], v[126:129]
	v_mfma_f32_16x16x32_bf16 v[122:125], v[170:173], v[194:197], v[122:125]
	v_mfma_f32_16x16x32_bf16 v[110:113], v[162:165], v[224:227], v[110:113]
	v_mfma_f32_16x16x32_bf16 v[106:109], v[170:173], v[224:227], v[106:109]
	v_mfma_f32_16x16x32_bf16 v[94:97], v[162:165], v[232:235], v[94:97]
	v_mfma_f32_16x16x32_bf16 v[90:93], v[170:173], v[232:235], v[90:93]
	v_mfma_f32_16x16x32_bf16 v[78:81], v[162:165], v[240:243], v[78:81]
	v_mfma_f32_16x16x32_bf16 v[74:77], v[170:173], v[240:243], v[74:77]
	v_mfma_f32_16x16x32_bf16 v[126:129], v[166:169], v[198:201], v[126:129]
	v_mfma_f32_16x16x32_bf16 v[122:125], v[174:177], v[198:201], v[122:125]
	v_mfma_f32_16x16x32_bf16 v[110:113], v[166:169], v[228:231], v[110:113]
	v_mfma_f32_16x16x32_bf16 v[106:109], v[174:177], v[228:231], v[106:109]
	v_mfma_f32_16x16x32_bf16 v[94:97], v[166:169], v[236:239], v[94:97]
	v_mfma_f32_16x16x32_bf16 v[90:93], v[174:177], v[236:239], v[90:93]
	v_mfma_f32_16x16x32_bf16 v[78:81], v[166:169], v[244:247], v[78:81]
	v_mfma_f32_16x16x32_bf16 v[74:77], v[174:177], v[244:247], v[74:77]
	v_mfma_f32_16x16x32_bf16 v[118:121], v[178:181], v[194:197], v[118:121]
	v_mfma_f32_16x16x32_bf16 v[114:117], v[186:189], v[194:197], v[114:117]
	v_mfma_f32_16x16x32_bf16 v[102:105], v[178:181], v[224:227], v[102:105]
	v_mfma_f32_16x16x32_bf16 v[98:101], v[186:189], v[224:227], v[98:101]
	v_mfma_f32_16x16x32_bf16 v[86:89], v[178:181], v[232:235], v[86:89]
	v_mfma_f32_16x16x32_bf16 v[82:85], v[186:189], v[232:235], v[82:85]
	v_mfma_f32_16x16x32_bf16 v[70:73], v[178:181], v[240:243], v[70:73]
	v_mfma_f32_16x16x32_bf16 v[66:69], v[186:189], v[240:243], v[66:69]
	v_mfma_f32_16x16x32_bf16 v[118:121], v[182:185], v[198:201], v[118:121]
	v_mfma_f32_16x16x32_bf16 v[114:117], v[190:193], v[198:201], v[114:117]
	v_mfma_f32_16x16x32_bf16 v[102:105], v[182:185], v[228:231], v[102:105]
	v_mfma_f32_16x16x32_bf16 v[98:101], v[190:193], v[228:231], v[98:101]
	v_mfma_f32_16x16x32_bf16 v[86:89], v[182:185], v[236:239], v[86:89]
	v_mfma_f32_16x16x32_bf16 v[82:85], v[190:193], v[236:239], v[82:85]
	v_mfma_f32_16x16x32_bf16 v[70:73], v[182:185], v[244:247], v[70:73]
	v_mfma_f32_16x16x32_bf16 v[66:69], v[190:193], v[244:247], v[66:69]
	s_barrier
	s_add_i32 s65, s65, s21
	v_lshl_add_u64 v[158:159], s[70:71], 0, v[0:1]
	s_mov_b32 m0, s65
	ds_read_b128 v[194:197], v161 offset:16384
	ds_read_b128 v[198:201], v161 offset:17408
	ds_read_b128 v[224:227], v161 offset:18432
	ds_read_b128 v[228:231], v161 offset:19456
	ds_read_b128 v[232:235], v161 offset:20480
	ds_read_b128 v[236:239], v161 offset:21504
	ds_read_b128 v[240:243], v161 offset:22528
	ds_read_b128 v[244:247], v161 offset:23552
	global_load_lds_dwordx4 v[158:159], off
	s_add_i32 m0, s65, 0x2000
	s_add_u32 s66, s70, 0x40000
	v_lshl_add_u64 v[202:203], s[70:71], 0, v[134:135]
	s_addc_u32 s67, s71, 0
	s_add_i32 s57, s57, s21
	global_load_lds_dwordx4 v[202:203], off
	v_lshl_add_u64 v[210:211], s[66:67], 0, v[0:1]
	s_mov_b32 m0, s57
	v_lshl_add_u64 v[248:249], s[72:73], 0, v[132:133]
	global_load_lds_dwordx4 v[210:211], off
	v_lshl_add_u64 v[210:211], s[66:67], 0, v[134:135]
	s_add_i32 m0, s57, 0x2000
	s_nop 0
	global_load_lds_dwordx4 v[210:211], off
	v_lshl_add_u64 v[210:211], s[72:73], 0, v[130:131]
	s_mov_b32 m0, s35
	s_nop 0
	global_load_lds_dwordx4 v[210:211], off
	s_mov_b32 m0, s40
	s_nop 0
	global_load_lds_dwordx4 v[248:249], off
	s_waitcnt vmcnt(8)
	s_waitcnt lgkmcnt(0)
	s_barrier
; #define PG8_STAGE(bufoff, gbase, voff) do { _Pragma("unroll") for (int _i = 0; _i < 2; ++_i) \
;         __builtin_amdgcn_global_load_lds((const unsigned*)((const char*)(gbase) + (voff)[_i]), (LAS unsigned*)(lds + (bufoff) + ldsw + _i * 8192), 16, 0, 0); } while (0)
; #define PG8_LDA(dst, b, h) do { _Pragma("unroll") for (int m = 0; m < 4; ++m) _Pragma("unroll") for (int k = 0; k < 2; ++k) dst[m][k] = *(const LAS bf16x8*)(lds + PG8_SA(b, h) + aoff + m * 2048 + k * 1024); } while (0)
; #define PG8_LDB(dst, b, h) do { _Pragma("unroll") for (int n = 0; n < 2; ++n) _Pragma("unroll") for (int k = 0; k < 2; ++k) dst[n][k] = *(const LAS bf16x8*)(lds + PG8_SB(b, h) + boff + n * 2048 + k * 1024); } while (0)
; #define PG8_MMA(ai, bj, At, Bt) do { __builtin_amdgcn_s_setprio(1); _Pragma("unroll") for (int m = 0; m < 4; ++m) _Pragma("unroll") for (int n = 0; n < 2; ++n) _Pragma("unroll") for (int k = 0; k < 2; ++k) \
;         acc[ai][bj][m][n] = __builtin_amdgcn_mfma_f32_16x16x32_bf16(Bt[n][k], At[m][k], acc[ai][bj][m][n], 0, 0, 0); __builtin_amdgcn_s_setprio(0); } while (0)
; #define PG8_WAIT_V(n) asm volatile("s_waitcnt vmcnt(" #n ")" ::: "memory")
; #define PG8_WAIT_L(n) asm volatile("s_waitcnt lgkmcnt(" #n ")" ::: "memory")
; #define PG8_BAR __builtin_amdgcn_s_barrier()
; #define PG8_SCHED __builtin_amdgcn_sched_barrier(0)
; template <class Epi, bool ALIGN_EPI = true, bool SP2 = true>
; __device__ __forceinline__ void gemm_phase(LAS unsigned char* lds, const Gemm g, const Order& S, const Epi& E) {
;     ...
;             PG8_WAIT_V(8); PG8_WAIT_L(0); PG8_BAR; PG8_MMA(1, 0, At, B0); PG8_MMA(1, 1, At, B1); PG8_BAR; PG8_SCHED;
;             PG8_LDB(B0, 1, 0); PG8_LDB(B1, 1, 1); PG8_SCHED; PG8_LDA(At, 1, 0); PG8_STAGE(PG8_SA(0, 1), a2 + hstepA, voffA);
;             PG8_WAIT_V(8); PG8_WAIT_L(0); PG8_BAR; PG8_MMA(0, 0, At, B0); PG8_MMA(0, 1, At, B1); PG8_BAR; PG8_SCHED;
	s_waitcnt lgkmcnt(0)
	v_mfma_f32_16x16x32_bf16 v[62:65], v[162:165], v[194:197], v[62:65]
	v_mfma_f32_16x16x32_bf16 v[58:61], v[170:173], v[194:197], v[58:61]
	v_mfma_f32_16x16x32_bf16 v[46:49], v[162:165], v[224:227], v[46:49]
	v_mfma_f32_16x16x32_bf16 v[42:45], v[170:173], v[224:227], v[42:45]
	v_mfma_f32_16x16x32_bf16 v[30:33], v[162:165], v[232:235], v[30:33]
	v_mfma_f32_16x16x32_bf16 v[26:29], v[170:173], v[232:235], v[26:29]
	v_mfma_f32_16x16x32_bf16 v[14:17], v[162:165], v[240:243], v[14:17]
	v_mfma_f32_16x16x32_bf16 v[10:13], v[170:173], v[240:243], v[10:13]
	v_mfma_f32_16x16x32_bf16 v[62:65], v[166:169], v[198:201], v[62:65]
	v_mfma_f32_16x16x32_bf16 v[58:61], v[174:177], v[198:201], v[58:61]
	v_mfma_f32_16x16x32_bf16 v[46:49], v[166:169], v[228:231], v[46:49]
	v_mfma_f32_16x16x32_bf16 v[42:45], v[174:177], v[228:231], v[42:45]
	v_mfma_f32_16x16x32_bf16 v[30:33], v[166:169], v[236:239], v[30:33]
	v_mfma_f32_16x16x32_bf16 v[26:29], v[174:177], v[236:239], v[26:29]
	v_mfma_f32_16x16x32_bf16 v[14:17], v[166:169], v[244:247], v[14:17]
	v_mfma_f32_16x16x32_bf16 v[10:13], v[174:177], v[244:247], v[10:13]
	v_mfma_f32_16x16x32_bf16 v[54:57], v[178:181], v[194:197], v[54:57]
	v_mfma_f32_16x16x32_bf16 v[50:53], v[186:189], v[194:197], v[50:53]
	v_mfma_f32_16x16x32_bf16 v[38:41], v[178:181], v[224:227], v[38:41]
	v_mfma_f32_16x16x32_bf16 v[34:37], v[186:189], v[224:227], v[34:37]
	v_mfma_f32_16x16x32_bf16 v[22:25], v[178:181], v[232:235], v[22:25]
	v_mfma_f32_16x16x32_bf16 v[18:21], v[186:189], v[232:235], v[18:21]
	v_mfma_f32_16x16x32_bf16 v[6:9], v[178:181], v[240:243], v[6:9]
	v_mfma_f32_16x16x32_bf16 v[2:5], v[186:189], v[240:243], v[2:5]
	v_mfma_f32_16x16x32_bf16 v[54:57], v[182:185], v[198:201], v[54:57]
	v_mfma_f32_16x16x32_bf16 v[50:53], v[190:193], v[198:201], v[50:53]
	v_mfma_f32_16x16x32_bf16 v[38:41], v[182:185], v[228:231], v[38:41]
	v_mfma_f32_16x16x32_bf16 v[34:37], v[190:193], v[228:231], v[34:37]
	v_mfma_f32_16x16x32_bf16 v[22:25], v[182:185], v[236:239], v[22:25]
	v_mfma_f32_16x16x32_bf16 v[18:21], v[190:193], v[236:239], v[18:21]
	v_mfma_f32_16x16x32_bf16 v[6:9], v[182:185], v[244:247], v[6:9]
	v_mfma_f32_16x16x32_bf16 v[2:5], v[190:193], v[244:247], v[2:5]
	s_barrier
	s_add_i32 s57, 0, 0x18000
	s_add_i32 s65, 0, 0x1c000
	v_add_u32_e32 v174, s57, v160
	v_add_u32_e32 v190, s65, v160
	ds_read_b128 v[162:165], v174
	ds_read_b128 v[166:169], v174 offset:1024
	ds_read_b128 v[170:173], v174 offset:2048
	ds_read_b128 v[174:177], v174 offset:3072
	ds_read_b128 v[178:181], v190
	ds_read_b128 v[182:185], v190 offset:1024
	ds_read_b128 v[186:189], v190 offset:2048
	ds_read_b128 v[190:193], v190 offset:3072
	s_add_u32 s66, s72, 0x140000
	s_addc_u32 s67, s73, 0
	s_mov_b32 m0, s42
	v_lshl_add_u64 v[250:251], s[66:67], 0, v[130:131]
	ds_read_b128 v[194:197], v161 offset:32768
	ds_read_b128 v[198:201], v161 offset:33792
	ds_read_b128 v[224:227], v161 offset:34816
	ds_read_b128 v[228:231], v161 offset:35840
	ds_read_b128 v[232:235], v161 offset:36864
	ds_read_b128 v[236:239], v161 offset:37888
	ds_read_b128 v[240:243], v161 offset:38912
	ds_read_b128 v[244:247], v161 offset:39936
	global_load_lds_dwordx4 v[250:251], off
	v_lshl_add_u64 v[250:251], s[66:67], 0, v[132:133]
	s_mov_b32 m0, s44
	s_nop 0
	global_load_lds_dwordx4 v[250:251], off
	s_waitcnt vmcnt(8)
	s_waitcnt lgkmcnt(0)
	s_barrier
	s_waitcnt lgkmcnt(0)
	v_mfma_f32_16x16x32_bf16 v[126:129], v[162:165], v[194:197], v[126:129]
	v_mfma_f32_16x16x32_bf16 v[122:125], v[170:173], v[194:197], v[122:125]
	v_mfma_f32_16x16x32_bf16 v[110:113], v[162:165], v[224:227], v[110:113]
	v_mfma_f32_16x16x32_bf16 v[106:109], v[170:173], v[224:227], v[106:109]
	v_mfma_f32_16x16x32_bf16 v[94:97], v[162:165], v[232:235], v[94:97]
	v_mfma_f32_16x16x32_bf16 v[90:93], v[170:173], v[232:235], v[90:93]
	v_mfma_f32_16x16x32_bf16 v[78:81], v[162:165], v[240:243], v[78:81]
	v_mfma_f32_16x16x32_bf16 v[74:77], v[170:173], v[240:243], v[74:77]
	v_mfma_f32_16x16x32_bf16 v[126:129], v[166:169], v[198:201], v[126:129]
	v_mfma_f32_16x16x32_bf16 v[122:125], v[174:177], v[198:201], v[122:125]
	v_mfma_f32_16x16x32_bf16 v[110:113], v[166:169], v[228:231], v[110:113]
	v_mfma_f32_16x16x32_bf16 v[106:109], v[174:177], v[228:231], v[106:109]
	v_mfma_f32_16x16x32_bf16 v[94:97], v[166:169], v[236:239], v[94:97]
	v_mfma_f32_16x16x32_bf16 v[90:93], v[174:177], v[236:239], v[90:93]
	v_mfma_f32_16x16x32_bf16 v[78:81], v[166:169], v[244:247], v[78:81]
	v_mfma_f32_16x16x32_bf16 v[74:77], v[174:177], v[244:247], v[74:77]
	v_mfma_f32_16x16x32_bf16 v[118:121], v[178:181], v[194:197], v[118:121]
	v_mfma_f32_16x16x32_bf16 v[114:117], v[186:189], v[194:197], v[114:117]
	v_mfma_f32_16x16x32_bf16 v[102:105], v[178:181], v[224:227], v[102:105]
	v_mfma_f32_16x16x32_bf16 v[98:101], v[186:189], v[224:227], v[98:101]
	v_mfma_f32_16x16x32_bf16 v[86:89], v[178:181], v[232:235], v[86:89]
	v_mfma_f32_16x16x32_bf16 v[82:85], v[186:189], v[232:235], v[82:85]
	v_mfma_f32_16x16x32_bf16 v[70:73], v[178:181], v[240:243], v[70:73]
	v_mfma_f32_16x16x32_bf16 v[66:69], v[186:189], v[240:243], v[66:69]
	v_mfma_f32_16x16x32_bf16 v[118:121], v[182:185], v[198:201], v[118:121]
	v_mfma_f32_16x16x32_bf16 v[114:117], v[190:193], v[198:201], v[114:117]
	v_mfma_f32_16x16x32_bf16 v[102:105], v[182:185], v[228:231], v[102:105]
	v_mfma_f32_16x16x32_bf16 v[98:101], v[190:193], v[228:231], v[98:101]
	v_mfma_f32_16x16x32_bf16 v[86:89], v[182:185], v[236:239], v[86:89]
	v_mfma_f32_16x16x32_bf16 v[82:85], v[190:193], v[236:239], v[82:85]
	v_mfma_f32_16x16x32_bf16 v[70:73], v[182:185], v[244:247], v[70:73]
	v_mfma_f32_16x16x32_bf16 v[66:69], v[190:193], v[244:247], v[66:69]
	s_barrier
; #define PG8_STAGE(bufoff, gbase, voff) do { _Pragma("unroll") for (int _i = 0; _i < 2; ++_i) \
;         __builtin_amdgcn_global_load_lds((const unsigned*)((const char*)(gbase) + (voff)[_i]), (LAS unsigned*)(lds + (bufoff) + ldsw + _i * 8192), 16, 0, 0); } while (0)
; #define PG8_LDA(dst, b, h) do { _Pragma("unroll") for (int m = 0; m < 4; ++m) _Pragma("unroll") for (int k = 0; k < 2; ++k) dst[m][k] = *(const LAS bf16x8*)(lds + PG8_SA(b, h) + aoff + m * 2048 + k * 1024); } while (0)
; #define PG8_MMA(ai, bj, At, Bt) do { __builtin_amdgcn_s_setprio(1); _Pragma("unroll") for (int m = 0; m < 4; ++m) _Pragma("unroll") for (int n = 0; n < 2; ++n) _Pragma("unroll") for (int k = 0; k < 2; ++k) \
;         acc[ai][bj][m][n] = __builtin_amdgcn_mfma_f32_16x16x32_bf16(Bt[n][k], At[m][k], acc[ai][bj][m][n], 0, 0, 0); __builtin_amdgcn_s_setprio(0); } while (0)
; #define PG8_WAIT_V(n) asm volatile("s_waitcnt vmcnt(" #n ")" ::: "memory")
; #define PG8_WAIT_L(n) asm volatile("s_waitcnt lgkmcnt(" #n ")" ::: "memory")
; #define PG8_BAR __builtin_amdgcn_s_barrier()
; #define PG8_SCHED __builtin_amdgcn_sched_barrier(0)
; template <class Epi, bool ALIGN_EPI = true, bool SP2 = true>
; __device__ __forceinline__ void gemm_phase(LAS unsigned char* lds, const Gemm g, const Order& S, const Epi& E) {
;     ...
;             PG8_LDA(At, 1, 1); PG8_STAGE(PG8_SB(1, 0), b3, voffB); PG8_STAGE(PG8_SB(1, 1), b3 + hstepB, voffB); PG8_STAGE(PG8_SA(1, 0), a3, voffA);
;             PG8_WAIT_V(8); PG8_WAIT_L(0); PG8_BAR; PG8_MMA(1, 0, At, B0); PG8_MMA(1, 1, At, B1); PG8_BAR; PG8_SCHED;
;     ...
;         if constexpr (ALIGN_EPI) { if (wr == 0) PG8_BAR; }
	s_add_i32 s57, s57, s21
	v_lshl_add_u64 v[158:159], v[158:159], 0, s[26:27]
	s_mov_b32 m0, s57
	ds_read_b128 v[194:197], v161 offset:49152
	ds_read_b128 v[198:201], v161 offset:50176
	ds_read_b128 v[224:227], v161 offset:51200
	ds_read_b128 v[228:231], v161 offset:52224
	ds_read_b128 v[232:235], v161 offset:53248
	ds_read_b128 v[236:239], v161 offset:54272
	ds_read_b128 v[240:243], v161 offset:55296
	ds_read_b128 v[244:247], v161 offset:56320
	global_load_lds_dwordx4 v[158:159], off
	s_add_i32 m0, s57, 0x2000
	s_add_u32 s66, s70, 0x40080
	v_lshl_add_u64 v[158:159], v[202:203], 0, s[26:27]
	s_addc_u32 s67, s71, 0
	s_add_i32 s57, s65, s21
	global_load_lds_dwordx4 v[158:159], off
	v_lshl_add_u64 v[158:159], s[66:67], 0, v[0:1]
	s_mov_b32 m0, s57
	s_nop 0
	global_load_lds_dwordx4 v[158:159], off
	v_lshl_add_u64 v[158:159], s[66:67], 0, v[134:135]
	s_add_i32 m0, s57, 0x2000
	s_nop 0
	global_load_lds_dwordx4 v[158:159], off
	v_lshl_add_u64 v[158:159], v[210:211], 0, s[26:27]
	s_mov_b32 m0, s48
	s_nop 0
	global_load_lds_dwordx4 v[158:159], off
	v_lshl_add_u64 v[158:159], v[248:249], 0, s[26:27]
	s_mov_b32 m0, s49
	s_nop 0
	global_load_lds_dwordx4 v[158:159], off
	s_waitcnt vmcnt(8)
	s_waitcnt lgkmcnt(0)
	s_barrier
	s_waitcnt lgkmcnt(0)
	v_mfma_f32_16x16x32_bf16 v[62:65], v[162:165], v[194:197], v[62:65]
	v_mfma_f32_16x16x32_bf16 v[58:61], v[170:173], v[194:197], v[58:61]
	v_mfma_f32_16x16x32_bf16 v[46:49], v[162:165], v[224:227], v[46:49]
	v_mfma_f32_16x16x32_bf16 v[42:45], v[170:173], v[224:227], v[42:45]
	v_mfma_f32_16x16x32_bf16 v[30:33], v[162:165], v[232:235], v[30:33]
	v_mfma_f32_16x16x32_bf16 v[26:29], v[170:173], v[232:235], v[26:29]
	v_mfma_f32_16x16x32_bf16 v[14:17], v[162:165], v[240:243], v[14:17]
	v_mfma_f32_16x16x32_bf16 v[10:13], v[170:173], v[240:243], v[10:13]
	v_mfma_f32_16x16x32_bf16 v[62:65], v[166:169], v[198:201], v[62:65]
	v_mfma_f32_16x16x32_bf16 v[58:61], v[174:177], v[198:201], v[58:61]
	v_mfma_f32_16x16x32_bf16 v[46:49], v[166:169], v[228:231], v[46:49]
	v_mfma_f32_16x16x32_bf16 v[42:45], v[174:177], v[228:231], v[42:45]
	v_mfma_f32_16x16x32_bf16 v[30:33], v[166:169], v[236:239], v[30:33]
	v_mfma_f32_16x16x32_bf16 v[26:29], v[174:177], v[236:239], v[26:29]
	v_mfma_f32_16x16x32_bf16 v[14:17], v[166:169], v[244:247], v[14:17]
	v_mfma_f32_16x16x32_bf16 v[10:13], v[174:177], v[244:247], v[10:13]
	v_mfma_f32_16x16x32_bf16 v[54:57], v[178:181], v[194:197], v[54:57]
	v_mfma_f32_16x16x32_bf16 v[50:53], v[186:189], v[194:197], v[50:53]
	v_mfma_f32_16x16x32_bf16 v[38:41], v[178:181], v[224:227], v[38:41]
	v_mfma_f32_16x16x32_bf16 v[34:37], v[186:189], v[224:227], v[34:37]
	v_mfma_f32_16x16x32_bf16 v[22:25], v[178:181], v[232:235], v[22:25]
	v_mfma_f32_16x16x32_bf16 v[18:21], v[186:189], v[232:235], v[18:21]
	v_mfma_f32_16x16x32_bf16 v[6:9], v[178:181], v[240:243], v[6:9]
	v_mfma_f32_16x16x32_bf16 v[2:5], v[186:189], v[240:243], v[2:5]
	v_mfma_f32_16x16x32_bf16 v[54:57], v[182:185], v[198:201], v[54:57]
	v_mfma_f32_16x16x32_bf16 v[50:53], v[190:193], v[198:201], v[50:53]
	v_mfma_f32_16x16x32_bf16 v[38:41], v[182:185], v[228:231], v[38:41]
	v_mfma_f32_16x16x32_bf16 v[34:37], v[190:193], v[228:231], v[34:37]
	v_mfma_f32_16x16x32_bf16 v[22:25], v[182:185], v[236:239], v[22:25]
	v_mfma_f32_16x16x32_bf16 v[18:21], v[190:193], v[236:239], v[18:21]
	v_mfma_f32_16x16x32_bf16 v[6:9], v[182:185], v[244:247], v[6:9]
	v_mfma_f32_16x16x32_bf16 v[2:5], v[190:193], v[244:247], v[2:5]
	s_barrier
	s_add_u32 s15, s15, 0x100
	s_addc_u32 s55, s55, 0
	s_cmp_ge_i32 s63, s54
	s_mov_b64 s[66:67], s[68:69]
	s_mov_b32 s57, s63
	s_cbranch_scc0 .LBB0_724
	s_setprio 0
	s_and_b64 vcc, exec, s[10:11]
	s_cbranch_vccz .LBB0_732

; template <class Epi, bool ALIGN_EPI = true, bool SP2 = true>
; __device__ __forceinline__ void gemm_phase(LAS unsigned char* lds, const Gemm g, const Order& S, const Epi& E) {
;     ...
;         const bool has_next = S.next(ui + 1, nxt);
;         const char* nA = has_next ? (const char*)(nxt.z ? g.A1 : g.A0) + (size_t)nxt.pm * tstepA + (size_t)nxt.kt0 * kstep : cA; const char* nB = has_next ? (const char*)(nxt.z ? g.B1 : g.B0) + (size_t)nxt.pn * tstepB + (size_t)nxt.kt0 * kstep : cB;
;         const int nt = cur.nkt;
;     ...
;         for (int a = 0; a < 2; ++a)
; #pragma unroll
;             for (int b = 0; b < 2; ++b)
; #pragma unroll
;                 for (int m = 0; m < 4; ++m)
; #pragma unroll
;                     for (int n = 0; n < 2; ++n) acc[a][b][m][n] = (f32x4){0.f, 0.f, 0.f, 0.f};
.LBB0_879:
	s_ashr_i32 s85, s84, 31
	s_lshl_b64 s[54:55], s[84:85], 19
	s_add_u32 s11, s50, s54
	s_addc_u32 s35, s51, s55
	s_and_b64 s[54:55], s[88:89], exec
	s_cselect_b32 s87, s35, s13
	s_cselect_b32 s86, s11, s12
	s_ashr_i32 s83, s82, 31
	s_lshl_b64 s[54:55], s[82:83], 19
	s_add_u32 s11, s52, s54
	s_addc_u32 s35, s53, s55
	s_and_b64 s[54:55], s[88:89], exec
	s_cselect_b32 s89, s35, s93
	s_cselect_b32 s88, s11, s92
	s_add_u32 s12, s12, 0x40080
	s_addc_u32 s13, s13, 0
	s_add_u32 s11, s92, 0x100
	v_mov_b32_e32 v2, 0
	s_addc_u32 s35, s93, 0
	s_mov_b32 s54, -2
	v_mov_b32_e32 v3, v2
	v_mov_b32_e32 v4, v2
	v_mov_b32_e32 v5, v2
	v_mov_b32_e32 v14, v2
	v_mov_b32_e32 v15, v2
	v_mov_b32_e32 v16, v2
	v_mov_b32_e32 v17, v2
	v_mov_b32_e32 v18, v2
	v_mov_b32_e32 v19, v2
	v_mov_b32_e32 v20, v2
	v_mov_b32_e32 v21, v2
	v_mov_b32_e32 v30, v2
	v_mov_b32_e32 v31, v2
	v_mov_b32_e32 v32, v2
	v_mov_b32_e32 v33, v2
	v_mov_b32_e32 v34, v2
	v_mov_b32_e32 v35, v2
	v_mov_b32_e32 v36, v2
	v_mov_b32_e32 v37, v2
	v_mov_b32_e32 v46, v2
	v_mov_b32_e32 v47, v2
	v_mov_b32_e32 v48, v2
	v_mov_b32_e32 v49, v2
	v_mov_b32_e32 v82, v2
	v_mov_b32_e32 v83, v2
	v_mov_b32_e32 v84, v2
	v_mov_b32_e32 v85, v2
	v_mov_b32_e32 v94, v2
	v_mov_b32_e32 v95, v2
	v_mov_b32_e32 v96, v2
	v_mov_b32_e32 v97, v2
	v_mov_b32_e32 v6, v2
	v_mov_b32_e32 v7, v2
	v_mov_b32_e32 v8, v2
	v_mov_b32_e32 v9, v2
	v_mov_b32_e32 v10, v2
	v_mov_b32_e32 v11, v2
	v_mov_b32_e32 v12, v2
	v_mov_b32_e32 v13, v2
	v_mov_b32_e32 v22, v2
	v_mov_b32_e32 v23, v2
	v_mov_b32_e32 v24, v2
	v_mov_b32_e32 v25, v2
	v_mov_b32_e32 v26, v2
	v_mov_b32_e32 v27, v2
	v_mov_b32_e32 v28, v2
	v_mov_b32_e32 v29, v2
	v_mov_b32_e32 v38, v2
	v_mov_b32_e32 v39, v2
	v_mov_b32_e32 v40, v2
	v_mov_b32_e32 v41, v2
	v_mov_b32_e32 v42, v2
	v_mov_b32_e32 v43, v2
	v_mov_b32_e32 v44, v2
	v_mov_b32_e32 v45, v2
	v_mov_b32_e32 v86, v2
	v_mov_b32_e32 v87, v2
	v_mov_b32_e32 v88, v2
	v_mov_b32_e32 v89, v2
	v_mov_b32_e32 v90, v2
	v_mov_b32_e32 v91, v2
	v_mov_b32_e32 v92, v2
	v_mov_b32_e32 v93, v2
	v_mov_b32_e32 v106, v2
	v_mov_b32_e32 v107, v2
	v_mov_b32_e32 v108, v2
	v_mov_b32_e32 v109, v2
	v_mov_b32_e32 v114, v2
	v_mov_b32_e32 v115, v2
	v_mov_b32_e32 v116, v2
	v_mov_b32_e32 v117, v2
	v_mov_b32_e32 v122, v2
	v_mov_b32_e32 v123, v2
	v_mov_b32_e32 v124, v2
	v_mov_b32_e32 v125, v2
	v_mov_b32_e32 v130, v2
	v_mov_b32_e32 v131, v2
	v_mov_b32_e32 v132, v2
	v_mov_b32_e32 v133, v2
	v_mov_b32_e32 v138, v2
	v_mov_b32_e32 v139, v2
	v_mov_b32_e32 v140, v2
	v_mov_b32_e32 v141, v2
	v_mov_b32_e32 v146, v2
	v_mov_b32_e32 v147, v2
	v_mov_b32_e32 v148, v2
	v_mov_b32_e32 v149, v2
	v_mov_b32_e32 v154, v2
	v_mov_b32_e32 v155, v2
	v_mov_b32_e32 v156, v2
	v_mov_b32_e32 v157, v2
	v_mov_b32_e32 v158, v2
	v_mov_b32_e32 v159, v2
	v_mov_b32_e32 v160, v2
	v_mov_b32_e32 v161, v2
	v_mov_b32_e32 v98, v2
	v_mov_b32_e32 v99, v2
	v_mov_b32_e32 v100, v2
	v_mov_b32_e32 v101, v2
	v_mov_b32_e32 v102, v2
	v_mov_b32_e32 v103, v2
	v_mov_b32_e32 v104, v2
	v_mov_b32_e32 v105, v2
	v_mov_b32_e32 v110, v2
	v_mov_b32_e32 v111, v2
	v_mov_b32_e32 v112, v2
	v_mov_b32_e32 v113, v2
	v_mov_b32_e32 v118, v2
	v_mov_b32_e32 v119, v2
	v_mov_b32_e32 v120, v2
	v_mov_b32_e32 v121, v2
	v_mov_b32_e32 v126, v2
	v_mov_b32_e32 v127, v2
	v_mov_b32_e32 v128, v2
	v_mov_b32_e32 v129, v2
	v_mov_b32_e32 v134, v2
	v_mov_b32_e32 v135, v2
	v_mov_b32_e32 v136, v2
	v_mov_b32_e32 v137, v2
	v_mov_b32_e32 v142, v2
	v_mov_b32_e32 v143, v2
	v_mov_b32_e32 v144, v2
	v_mov_b32_e32 v145, v2
	v_mov_b32_e32 v150, v2
	v_mov_b32_e32 v151, v2
	v_mov_b32_e32 v152, v2
	v_mov_b32_e32 v153, v2
	s_cmp_lg_u32 s76, 0
	s_cbranch_scc1 .Lsprio_skip_3
	s_setprio 1

; #define PG8_STAGE(bufoff, gbase, voff) do { _Pragma("unroll") for (int _i = 0; _i < 2; ++_i) \
;         __builtin_amdgcn_global_load_lds((const unsigned*)((const char*)(gbase) + (voff)[_i]), (LAS unsigned*)(lds + (bufoff) + ldsw + _i * 8192), 16, 0, 0); } while (0)
; #define PG8_LDA(dst, b, h) do { _Pragma("unroll") for (int m = 0; m < 4; ++m) _Pragma("unroll") for (int k = 0; k < 2; ++k) dst[m][k] = *(const LAS bf16x8*)(lds + PG8_SA(b, h) + aoff + m * 2048 + k * 1024); } while (0)
; #define PG8_LDB(dst, b, h) do { _Pragma("unroll") for (int n = 0; n < 2; ++n) _Pragma("unroll") for (int k = 0; k < 2; ++k) dst[n][k] = *(const LAS bf16x8*)(lds + PG8_SB(b, h) + boff + n * 2048 + k * 1024); } while (0)
; #define PG8_MMA(ai, bj, At, Bt) do { __builtin_amdgcn_s_setprio(1); _Pragma("unroll") for (int m = 0; m < 4; ++m) _Pragma("unroll") for (int n = 0; n < 2; ++n) _Pragma("unroll") for (int k = 0; k < 2; ++k) \
;         acc[ai][bj][m][n] = __builtin_amdgcn_mfma_f32_16x16x32_bf16(Bt[n][k], At[m][k], acc[ai][bj][m][n], 0, 0, 0); __builtin_amdgcn_s_setprio(0); } while (0)
; #define PG8_WAIT_V(n) asm volatile("s_waitcnt vmcnt(" #n ")" ::: "memory")
; #define PG8_WAIT_L(n) asm volatile("s_waitcnt lgkmcnt(" #n ")" ::: "memory")
; #define PG8_BAR __builtin_amdgcn_s_barrier()
; #define PG8_SCHED __builtin_amdgcn_sched_barrier(0)
; template <class Epi, bool ALIGN_EPI = true, bool SP2 = true>
; __device__ __forceinline__ void gemm_phase(LAS unsigned char* lds, const Gemm g, const Order& S, const Epi& E) {
;     ...
;             const bool last = (t == nt - 2);
;             const char* a1 = cA + (size_t)(t + 1) * kstep;
;             const char* a2 = last ? nA : cA + (size_t)(t + 2) * kstep; const char* b2 = last ? nB : cB + (size_t)(t + 2) * kstep;
;             const char* a3 = a2 + kstep; const char* b3 = b2 + kstep;
;             if constexpr (SP2) {
;             PG8_LDB(B0, 0, 0); PG8_LDB(B1, 0, 1); PG8_SCHED; PG8_LDA(At, 0, 0); PG8_STAGE(PG8_SA(1, 1), a1 + hstepA, voffA);
;             PG8_WAIT_V(8); PG8_WAIT_L(0); PG8_BAR; PG8_MMA(0, 0, At, B0); PG8_MMA(0, 1, At, B1); PG8_BAR; PG8_SCHED;
;             PG8_LDA(At, 0, 1); PG8_STAGE(PG8_SB(0, 0), b2, voffB); PG8_STAGE(PG8_SB(0, 1), b2 + hstepB, voffB); PG8_STAGE(PG8_SA(0, 0), a2, voffA);
;             PG8_WAIT_V(8); PG8_WAIT_L(0); PG8_BAR; PG8_MMA(1, 0, At, B0); PG8_MMA(1, 1, At, B1); PG8_BAR; PG8_SCHED;
.LBB0_880:
	s_add_u32 s55, s12, 0xfffc0080
	s_addc_u32 s83, s13, -1
	s_add_i32 s85, 0, 0x10000
	s_cmp_eq_u32 s54, 12
	s_cselect_b32 s95, s87, s83
	s_cselect_b32 s94, s86, s55
	v_add_u32_e32 v0, s85, v179
	s_cselect_b32 s93, s89, s35
	s_cselect_b32 s92, s88, s11
	s_add_i32 s55, 0, 0x14000
	ds_read_b128 v[50:53], v0
	ds_read_b128 v[54:57], v0 offset:1024
	ds_read_b128 v[58:61], v0 offset:2048
	ds_read_b128 v[62:65], v0 offset:3072
	v_add_u32_e32 v0, s55, v179
	ds_read_b128 v[66:69], v0
	ds_read_b128 v[70:73], v0 offset:1024
	ds_read_b128 v[74:77], v0 offset:2048
	ds_read_b128 v[78:81], v0 offset:3072
	v_lshl_add_u64 v[210:211], s[12:13], 0, v[170:171]
	s_add_i32 m0, s46, 0xc000
	ds_read_b128 v[174:177], v182
	ds_read_b128 v[184:187], v182 offset:1024
	ds_read_b128 v[188:191], v182 offset:2048
	ds_read_b128 v[192:195], v182 offset:3072
	ds_read_b128 v[196:199], v182 offset:4096
	ds_read_b128 v[200:203], v182 offset:5120
	ds_read_b128 v[224:227], v182 offset:6144
	ds_read_b128 v[228:231], v182 offset:7168
	global_load_lds_dwordx4 v[210:211], off
	v_lshl_add_u64 v[210:211], s[12:13], 0, v[172:173]
	s_add_i32 m0, s46, 0xe000
	s_nop 0
	global_load_lds_dwordx4 v[210:211], off
	s_waitcnt vmcnt(8)
	s_waitcnt lgkmcnt(0)
	s_barrier
	s_waitcnt lgkmcnt(0)
	v_mfma_f32_16x16x32_bf16 v[150:153], v[50:53], v[174:177], v[150:153]
	v_mfma_f32_16x16x32_bf16 v[142:145], v[58:61], v[174:177], v[142:145]
	v_mfma_f32_16x16x32_bf16 v[134:137], v[50:53], v[188:191], v[134:137]
	v_mfma_f32_16x16x32_bf16 v[126:129], v[58:61], v[188:191], v[126:129]
	v_mfma_f32_16x16x32_bf16 v[118:121], v[50:53], v[196:199], v[118:121]
	v_mfma_f32_16x16x32_bf16 v[110:113], v[58:61], v[196:199], v[110:113]
	v_mfma_f32_16x16x32_bf16 v[102:105], v[50:53], v[224:227], v[102:105]
	v_mfma_f32_16x16x32_bf16 v[98:101], v[58:61], v[224:227], v[98:101]
	v_mfma_f32_16x16x32_bf16 v[150:153], v[54:57], v[184:187], v[150:153]
	v_mfma_f32_16x16x32_bf16 v[142:145], v[62:65], v[184:187], v[142:145]
	v_mfma_f32_16x16x32_bf16 v[134:137], v[54:57], v[192:195], v[134:137]
	v_mfma_f32_16x16x32_bf16 v[126:129], v[62:65], v[192:195], v[126:129]
	v_mfma_f32_16x16x32_bf16 v[118:121], v[54:57], v[200:203], v[118:121]
	v_mfma_f32_16x16x32_bf16 v[110:113], v[62:65], v[200:203], v[110:113]
	v_mfma_f32_16x16x32_bf16 v[102:105], v[54:57], v[228:231], v[102:105]
	v_mfma_f32_16x16x32_bf16 v[98:101], v[62:65], v[228:231], v[98:101]
	v_mfma_f32_16x16x32_bf16 v[158:161], v[66:69], v[174:177], v[158:161]
	v_mfma_f32_16x16x32_bf16 v[154:157], v[74:77], v[174:177], v[154:157]
	v_mfma_f32_16x16x32_bf16 v[146:149], v[66:69], v[188:191], v[146:149]
	v_mfma_f32_16x16x32_bf16 v[138:141], v[74:77], v[188:191], v[138:141]
	v_mfma_f32_16x16x32_bf16 v[130:133], v[66:69], v[196:199], v[130:133]
	v_mfma_f32_16x16x32_bf16 v[122:125], v[74:77], v[196:199], v[122:125]
	v_mfma_f32_16x16x32_bf16 v[114:117], v[66:69], v[224:227], v[114:117]
	v_mfma_f32_16x16x32_bf16 v[106:109], v[74:77], v[224:227], v[106:109]
	v_mfma_f32_16x16x32_bf16 v[158:161], v[70:73], v[184:187], v[158:161]
	v_mfma_f32_16x16x32_bf16 v[154:157], v[78:81], v[184:187], v[154:157]
	v_mfma_f32_16x16x32_bf16 v[146:149], v[70:73], v[192:195], v[146:149]
	v_mfma_f32_16x16x32_bf16 v[138:141], v[78:81], v[192:195], v[138:141]
	v_mfma_f32_16x16x32_bf16 v[130:133], v[70:73], v[200:203], v[130:133]
	v_mfma_f32_16x16x32_bf16 v[122:125], v[78:81], v[200:203], v[122:125]
	v_mfma_f32_16x16x32_bf16 v[114:117], v[70:73], v[228:231], v[114:117]
	v_mfma_f32_16x16x32_bf16 v[106:109], v[78:81], v[228:231], v[106:109]
	s_barrier
	s_add_i32 s83, s85, s49
	v_lshl_add_u64 v[210:211], s[92:93], 0, v[164:165]
	s_mov_b32 m0, s83
	ds_read_b128 v[174:177], v182 offset:16384
	ds_read_b128 v[184:187], v182 offset:17408
	ds_read_b128 v[188:191], v182 offset:18432
	ds_read_b128 v[192:195], v182 offset:19456
	ds_read_b128 v[196:199], v182 offset:20480
	ds_read_b128 v[200:203], v182 offset:21504
	ds_read_b128 v[224:227], v182 offset:22528
	ds_read_b128 v[228:231], v182 offset:23552
	global_load_lds_dwordx4 v[210:211], off
	s_add_i32 m0, s83, 0x2000
	s_add_u32 vcc_lo, s92, 0x40000
	v_lshl_add_u64 v[236:237], s[92:93], 0, v[168:169]
	s_addc_u32 vcc_hi, s93, 0
	s_add_i32 s55, s55, s49
	global_load_lds_dwordx4 v[236:237], off
	v_lshl_add_u64 v[232:233], vcc, 0, v[164:165]
	s_mov_b32 m0, s55
	v_lshl_add_u64 v[238:239], s[94:95], 0, v[162:163]
	global_load_lds_dwordx4 v[232:233], off
	v_lshl_add_u64 v[232:233], vcc, 0, v[168:169]
	s_add_i32 m0, s55, 0x2000
	v_lshl_add_u64 v[240:241], s[94:95], 0, v[166:167]
	global_load_lds_dwordx4 v[232:233], off
	s_mov_b32 m0, s46
	s_nop 0
	global_load_lds_dwordx4 v[238:239], off
	s_mov_b32 m0, s40
	s_nop 0
	global_load_lds_dwordx4 v[240:241], off
	s_waitcnt vmcnt(8)
	s_waitcnt lgkmcnt(0)
	s_barrier
; #define PG8_STAGE(bufoff, gbase, voff) do { _Pragma("unroll") for (int _i = 0; _i < 2; ++_i) \
;         __builtin_amdgcn_global_load_lds((const unsigned*)((const char*)(gbase) + (voff)[_i]), (LAS unsigned*)(lds + (bufoff) + ldsw + _i * 8192), 16, 0, 0); } while (0)
; #define PG8_LDA(dst, b, h) do { _Pragma("unroll") for (int m = 0; m < 4; ++m) _Pragma("unroll") for (int k = 0; k < 2; ++k) dst[m][k] = *(const LAS bf16x8*)(lds + PG8_SA(b, h) + aoff + m * 2048 + k * 1024); } while (0)
; #define PG8_LDB(dst, b, h) do { _Pragma("unroll") for (int n = 0; n < 2; ++n) _Pragma("unroll") for (int k = 0; k < 2; ++k) dst[n][k] = *(const LAS bf16x8*)(lds + PG8_SB(b, h) + boff + n * 2048 + k * 1024); } while (0)
; #define PG8_MMA(ai, bj, At, Bt) do { __builtin_amdgcn_s_setprio(1); _Pragma("unroll") for (int m = 0; m < 4; ++m) _Pragma("unroll") for (int n = 0; n < 2; ++n) _Pragma("unroll") for (int k = 0; k < 2; ++k) \
;         acc[ai][bj][m][n] = __builtin_amdgcn_mfma_f32_16x16x32_bf16(Bt[n][k], At[m][k], acc[ai][bj][m][n], 0, 0, 0); __builtin_amdgcn_s_setprio(0); } while (0)
; #define PG8_WAIT_V(n) asm volatile("s_waitcnt vmcnt(" #n ")" ::: "memory")
; #define PG8_WAIT_L(n) asm volatile("s_waitcnt lgkmcnt(" #n ")" ::: "memory")
; #define PG8_BAR __builtin_amdgcn_s_barrier()
; #define PG8_SCHED __builtin_amdgcn_sched_barrier(0)
; template <class Epi, bool ALIGN_EPI = true, bool SP2 = true>
; __device__ __forceinline__ void gemm_phase(LAS unsigned char* lds, const Gemm g, const Order& S, const Epi& E) {
;     ...
;             PG8_WAIT_V(8); PG8_WAIT_L(0); PG8_BAR; PG8_MMA(1, 0, At, B0); PG8_MMA(1, 1, At, B1); PG8_BAR; PG8_SCHED;
;             PG8_LDB(B0, 1, 0); PG8_LDB(B1, 1, 1); PG8_SCHED; PG8_LDA(At, 1, 0); PG8_STAGE(PG8_SA(0, 1), a2 + hstepA, voffA);
;             PG8_WAIT_V(8); PG8_WAIT_L(0); PG8_BAR; PG8_MMA(0, 0, At, B0); PG8_MMA(0, 1, At, B1); PG8_BAR; PG8_SCHED;
	s_waitcnt lgkmcnt(0)
	v_mfma_f32_16x16x32_bf16 v[90:93], v[50:53], v[174:177], v[90:93]
	v_mfma_f32_16x16x32_bf16 v[86:89], v[58:61], v[174:177], v[86:89]
	v_mfma_f32_16x16x32_bf16 v[42:45], v[50:53], v[188:191], v[42:45]
	v_mfma_f32_16x16x32_bf16 v[38:41], v[58:61], v[188:191], v[38:41]
	v_mfma_f32_16x16x32_bf16 v[26:29], v[50:53], v[196:199], v[26:29]
	v_mfma_f32_16x16x32_bf16 v[22:25], v[58:61], v[196:199], v[22:25]
	v_mfma_f32_16x16x32_bf16 v[10:13], v[50:53], v[224:227], v[10:13]
	v_mfma_f32_16x16x32_bf16 v[6:9], v[58:61], v[224:227], v[6:9]
	v_mfma_f32_16x16x32_bf16 v[90:93], v[54:57], v[184:187], v[90:93]
	v_mfma_f32_16x16x32_bf16 v[86:89], v[62:65], v[184:187], v[86:89]
	v_mfma_f32_16x16x32_bf16 v[42:45], v[54:57], v[192:195], v[42:45]
	v_mfma_f32_16x16x32_bf16 v[38:41], v[62:65], v[192:195], v[38:41]
	v_mfma_f32_16x16x32_bf16 v[26:29], v[54:57], v[200:203], v[26:29]
	v_mfma_f32_16x16x32_bf16 v[22:25], v[62:65], v[200:203], v[22:25]
	v_mfma_f32_16x16x32_bf16 v[10:13], v[54:57], v[228:231], v[10:13]
	v_mfma_f32_16x16x32_bf16 v[6:9], v[62:65], v[228:231], v[6:9]
	v_mfma_f32_16x16x32_bf16 v[46:49], v[66:69], v[188:191], v[46:49]
	v_mfma_f32_16x16x32_bf16 v[34:37], v[74:77], v[188:191], v[34:37]
	v_mfma_f32_16x16x32_bf16 v[30:33], v[66:69], v[196:199], v[30:33]
	v_mfma_f32_16x16x32_bf16 v[18:21], v[74:77], v[196:199], v[18:21]
	v_mfma_f32_16x16x32_bf16 v[14:17], v[66:69], v[224:227], v[14:17]
	v_mfma_f32_16x16x32_bf16 v[2:5], v[74:77], v[224:227], v[2:5]
	v_mfma_f32_16x16x32_bf16 v[50:53], v[66:69], v[174:177], v[94:97]
	v_mfma_f32_16x16x32_bf16 v[54:57], v[74:77], v[174:177], v[82:85]
	v_mfma_f32_16x16x32_bf16 v[46:49], v[70:73], v[192:195], v[46:49]
	v_mfma_f32_16x16x32_bf16 v[34:37], v[78:81], v[192:195], v[34:37]
	v_mfma_f32_16x16x32_bf16 v[30:33], v[70:73], v[200:203], v[30:33]
	v_mfma_f32_16x16x32_bf16 v[18:21], v[78:81], v[200:203], v[18:21]
	v_mfma_f32_16x16x32_bf16 v[14:17], v[70:73], v[228:231], v[14:17]
	v_mfma_f32_16x16x32_bf16 v[2:5], v[78:81], v[228:231], v[2:5]
	v_mfma_f32_16x16x32_bf16 v[50:53], v[70:73], v[184:187], v[50:53]
	v_mfma_f32_16x16x32_bf16 v[54:57], v[78:81], v[184:187], v[54:57]
	s_barrier
	s_add_i32 s55, 0, 0x18000
	v_add_u32_e32 v0, s55, v179
	s_add_i32 s83, 0, 0x1c000
	ds_read_b128 v[58:61], v0
	ds_read_b128 v[62:65], v0 offset:1024
	ds_read_b128 v[66:69], v0 offset:2048
	ds_read_b128 v[70:73], v0 offset:3072
	v_add_u32_e32 v0, s83, v179
	ds_read_b128 v[74:77], v0
	ds_read_b128 v[78:81], v0 offset:1024
	ds_read_b128 v[174:177], v0 offset:2048
	ds_read_b128 v[184:187], v0 offset:3072
	s_add_u32 s94, s94, 0x40000
	s_addc_u32 s95, s95, 0
	s_mov_b32 m0, s42
	v_lshl_add_u64 v[232:233], s[94:95], 0, v[162:163]
	ds_read_b128 v[82:85], v182 offset:32768
	ds_read_b128 v[94:97], v182 offset:33792
	ds_read_b128 v[188:191], v182 offset:34816
	ds_read_b128 v[192:195], v182 offset:35840
	ds_read_b128 v[196:199], v182 offset:36864
	ds_read_b128 v[200:203], v182 offset:37888
	ds_read_b128 v[224:227], v182 offset:38912
	ds_read_b128 v[228:231], v182 offset:39936
	global_load_lds_dwordx4 v[232:233], off
	v_lshl_add_u64 v[232:233], s[94:95], 0, v[166:167]
	s_mov_b32 m0, s44
	s_nop 0
	global_load_lds_dwordx4 v[232:233], off
	s_waitcnt vmcnt(8)
	s_waitcnt lgkmcnt(0)
	s_barrier
	s_waitcnt lgkmcnt(0)
	v_mfma_f32_16x16x32_bf16 v[150:153], v[58:61], v[82:85], v[150:153]
	v_mfma_f32_16x16x32_bf16 v[142:145], v[66:69], v[82:85], v[142:145]
	v_mfma_f32_16x16x32_bf16 v[134:137], v[58:61], v[188:191], v[134:137]
	v_mfma_f32_16x16x32_bf16 v[126:129], v[66:69], v[188:191], v[126:129]
	v_mfma_f32_16x16x32_bf16 v[118:121], v[58:61], v[196:199], v[118:121]
	v_mfma_f32_16x16x32_bf16 v[110:113], v[66:69], v[196:199], v[110:113]
	v_mfma_f32_16x16x32_bf16 v[102:105], v[58:61], v[224:227], v[102:105]
	v_mfma_f32_16x16x32_bf16 v[98:101], v[66:69], v[224:227], v[98:101]
	v_mfma_f32_16x16x32_bf16 v[150:153], v[62:65], v[94:97], v[150:153]
	v_mfma_f32_16x16x32_bf16 v[142:145], v[70:73], v[94:97], v[142:145]
	v_mfma_f32_16x16x32_bf16 v[134:137], v[62:65], v[192:195], v[134:137]
	v_mfma_f32_16x16x32_bf16 v[126:129], v[70:73], v[192:195], v[126:129]
	v_mfma_f32_16x16x32_bf16 v[118:121], v[62:65], v[200:203], v[118:121]
	v_mfma_f32_16x16x32_bf16 v[110:113], v[70:73], v[200:203], v[110:113]
	v_mfma_f32_16x16x32_bf16 v[102:105], v[62:65], v[228:231], v[102:105]
	v_mfma_f32_16x16x32_bf16 v[98:101], v[70:73], v[228:231], v[98:101]
	v_mfma_f32_16x16x32_bf16 v[158:161], v[74:77], v[82:85], v[158:161]
	v_mfma_f32_16x16x32_bf16 v[82:85], v[174:177], v[82:85], v[154:157]
	v_mfma_f32_16x16x32_bf16 v[154:157], v[184:187], v[94:97], v[82:85]
	v_mfma_f32_16x16x32_bf16 v[82:85], v[74:77], v[188:191], v[146:149]
	v_mfma_f32_16x16x32_bf16 v[146:149], v[78:81], v[192:195], v[82:85]
	v_mfma_f32_16x16x32_bf16 v[82:85], v[174:177], v[188:191], v[138:141]
	v_mfma_f32_16x16x32_bf16 v[138:141], v[184:187], v[192:195], v[82:85]
	v_mfma_f32_16x16x32_bf16 v[82:85], v[74:77], v[196:199], v[130:133]
	v_mfma_f32_16x16x32_bf16 v[130:133], v[78:81], v[200:203], v[82:85]
	v_mfma_f32_16x16x32_bf16 v[82:85], v[174:177], v[196:199], v[122:125]
	v_mfma_f32_16x16x32_bf16 v[122:125], v[184:187], v[200:203], v[82:85]
	v_mfma_f32_16x16x32_bf16 v[82:85], v[74:77], v[224:227], v[114:117]
	v_mfma_f32_16x16x32_bf16 v[114:117], v[78:81], v[228:231], v[82:85]
	v_mfma_f32_16x16x32_bf16 v[82:85], v[174:177], v[224:227], v[106:109]
	v_mfma_f32_16x16x32_bf16 v[158:161], v[78:81], v[94:97], v[158:161]
	v_mfma_f32_16x16x32_bf16 v[106:109], v[184:187], v[228:231], v[82:85]
	s_barrier
; #define PG8_STAGE(bufoff, gbase, voff) do { _Pragma("unroll") for (int _i = 0; _i < 2; ++_i) \
;         __builtin_amdgcn_global_load_lds((const unsigned*)((const char*)(gbase) + (voff)[_i]), (LAS unsigned*)(lds + (bufoff) + ldsw + _i * 8192), 16, 0, 0); } while (0)
; #define PG8_LDA(dst, b, h) do { _Pragma("unroll") for (int m = 0; m < 4; ++m) _Pragma("unroll") for (int k = 0; k < 2; ++k) dst[m][k] = *(const LAS bf16x8*)(lds + PG8_SA(b, h) + aoff + m * 2048 + k * 1024); } while (0)
; #define PG8_MMA(ai, bj, At, Bt) do { __builtin_amdgcn_s_setprio(1); _Pragma("unroll") for (int m = 0; m < 4; ++m) _Pragma("unroll") for (int n = 0; n < 2; ++n) _Pragma("unroll") for (int k = 0; k < 2; ++k) \
;         acc[ai][bj][m][n] = __builtin_amdgcn_mfma_f32_16x16x32_bf16(Bt[n][k], At[m][k], acc[ai][bj][m][n], 0, 0, 0); __builtin_amdgcn_s_setprio(0); } while (0)
; #define PG8_WAIT_V(n) asm volatile("s_waitcnt vmcnt(" #n ")" ::: "memory")
; #define PG8_WAIT_L(n) asm volatile("s_waitcnt lgkmcnt(" #n ")" ::: "memory")
; #define PG8_BAR __builtin_amdgcn_s_barrier()
; #define PG8_SCHED __builtin_amdgcn_sched_barrier(0)
; template <class Epi, bool ALIGN_EPI = true, bool SP2 = true>
; __device__ __forceinline__ void gemm_phase(LAS unsigned char* lds, const Gemm g, const Order& S, const Epi& E) {
;     ...
;             PG8_LDA(At, 1, 1); PG8_STAGE(PG8_SB(1, 0), b3, voffB); PG8_STAGE(PG8_SB(1, 1), b3 + hstepB, voffB); PG8_STAGE(PG8_SA(1, 0), a3, voffA);
;             PG8_WAIT_V(8); PG8_WAIT_L(0); PG8_BAR; PG8_MMA(1, 0, At, B0); PG8_MMA(1, 1, At, B1); PG8_BAR; PG8_SCHED;
;     ...
;         if constexpr (ALIGN_EPI) { if (wr == 0) PG8_BAR; }
	s_add_i32 s55, s55, s49
	v_lshl_add_u64 v[94:95], v[210:211], 0, s[26:27]
	s_mov_b32 m0, s55
	s_nop 0
	ds_read_b128 v[82:85], v182 offset:49152
	ds_read_b128 v[188:191], v182 offset:50176
	ds_read_b128 v[192:195], v182 offset:51200
	ds_read_b128 v[196:199], v182 offset:52224
	ds_read_b128 v[200:203], v182 offset:53248
	ds_read_b128 v[224:227], v182 offset:54272
	ds_read_b128 v[228:231], v182 offset:55296
	ds_read_b128 v[232:235], v182 offset:56320
	global_load_lds_dwordx4 v[94:95], off
	s_add_i32 m0, s55, 0x2000
	s_add_u32 s92, s92, 0x40080
	v_lshl_add_u64 v[94:95], v[236:237], 0, s[26:27]
	s_addc_u32 s93, s93, 0
	s_add_i32 s55, s83, s49
	global_load_lds_dwordx4 v[94:95], off
	v_lshl_add_u64 v[94:95], s[92:93], 0, v[164:165]
	s_mov_b32 m0, s55
	s_nop 0
	global_load_lds_dwordx4 v[94:95], off
	v_lshl_add_u64 v[94:95], s[92:93], 0, v[168:169]
	s_add_i32 m0, s55, 0x2000
	s_nop 0
	global_load_lds_dwordx4 v[94:95], off
	v_lshl_add_u64 v[94:95], v[238:239], 0, s[26:27]
	s_mov_b32 m0, s19
	s_nop 0
	global_load_lds_dwordx4 v[94:95], off
	v_lshl_add_u64 v[94:95], v[240:241], 0, s[26:27]
	s_mov_b32 m0, s45
	s_nop 0
	global_load_lds_dwordx4 v[94:95], off
	s_waitcnt vmcnt(8)
	s_waitcnt lgkmcnt(0)
	s_barrier
	s_waitcnt lgkmcnt(0)
	v_mfma_f32_16x16x32_bf16 v[90:93], v[58:61], v[82:85], v[90:93]
	v_mfma_f32_16x16x32_bf16 v[86:89], v[66:69], v[82:85], v[86:89]
	v_mfma_f32_16x16x32_bf16 v[42:45], v[58:61], v[192:195], v[42:45]
	v_mfma_f32_16x16x32_bf16 v[38:41], v[66:69], v[192:195], v[38:41]
	v_mfma_f32_16x16x32_bf16 v[26:29], v[58:61], v[200:203], v[26:29]
	v_mfma_f32_16x16x32_bf16 v[22:25], v[66:69], v[200:203], v[22:25]
	v_mfma_f32_16x16x32_bf16 v[10:13], v[58:61], v[228:231], v[10:13]
	v_mfma_f32_16x16x32_bf16 v[6:9], v[66:69], v[228:231], v[6:9]
	v_mfma_f32_16x16x32_bf16 v[90:93], v[62:65], v[188:191], v[90:93]
	v_mfma_f32_16x16x32_bf16 v[86:89], v[70:73], v[188:191], v[86:89]
	v_mfma_f32_16x16x32_bf16 v[42:45], v[62:65], v[196:199], v[42:45]
	v_mfma_f32_16x16x32_bf16 v[38:41], v[70:73], v[196:199], v[38:41]
	v_mfma_f32_16x16x32_bf16 v[26:29], v[62:65], v[224:227], v[26:29]
	v_mfma_f32_16x16x32_bf16 v[22:25], v[70:73], v[224:227], v[22:25]
	v_mfma_f32_16x16x32_bf16 v[10:13], v[62:65], v[232:235], v[10:13]
	v_mfma_f32_16x16x32_bf16 v[6:9], v[70:73], v[232:235], v[6:9]
	v_mfma_f32_16x16x32_bf16 v[50:53], v[74:77], v[82:85], v[50:53]
	v_mfma_f32_16x16x32_bf16 v[94:97], v[78:81], v[188:191], v[50:53]
	v_mfma_f32_16x16x32_bf16 v[50:53], v[174:177], v[82:85], v[54:57]
	v_mfma_f32_16x16x32_bf16 v[46:49], v[74:77], v[192:195], v[46:49]
	v_mfma_f32_16x16x32_bf16 v[34:37], v[174:177], v[192:195], v[34:37]
	v_mfma_f32_16x16x32_bf16 v[30:33], v[74:77], v[200:203], v[30:33]
	v_mfma_f32_16x16x32_bf16 v[18:21], v[174:177], v[200:203], v[18:21]
	v_mfma_f32_16x16x32_bf16 v[14:17], v[74:77], v[228:231], v[14:17]
	v_mfma_f32_16x16x32_bf16 v[2:5], v[174:177], v[228:231], v[2:5]
	v_mfma_f32_16x16x32_bf16 v[82:85], v[184:187], v[188:191], v[50:53]
	v_mfma_f32_16x16x32_bf16 v[46:49], v[78:81], v[196:199], v[46:49]
	v_mfma_f32_16x16x32_bf16 v[34:37], v[184:187], v[196:199], v[34:37]
	v_mfma_f32_16x16x32_bf16 v[30:33], v[78:81], v[224:227], v[30:33]
	v_mfma_f32_16x16x32_bf16 v[18:21], v[184:187], v[224:227], v[18:21]
	v_mfma_f32_16x16x32_bf16 v[14:17], v[78:81], v[232:235], v[14:17]
	v_mfma_f32_16x16x32_bf16 v[2:5], v[184:187], v[232:235], v[2:5]
	s_barrier
	s_add_i32 s54, s54, 2
	s_add_u32 s12, s12, 0x100
	s_addc_u32 s13, s13, 0
	s_add_u32 s11, s11, 0x100
	s_addc_u32 s35, s35, 0
	s_cmp_gt_u32 s54, 13
	s_cbranch_scc0 .LBB0_880
	s_setprio 0
	s_and_b64 vcc, exec, s[76:77]
	s_cbranch_vccz .LBB0_883
	s_barrier

; template <class Epi, bool ALIGN_EPI = true, bool SP2 = true>
; __device__ __forceinline__ void gemm_phase(LAS unsigned char* lds, const Gemm g, const Order& S, const Epi& E) {
;     ...
;         const int nt = cur.nkt;
;         for (int t = 0; t < nt; t += 2) {
;             const bool last = (t == nt - 2);
;             const char* a1 = cA + (size_t)(t + 1) * kstep;
;             const char* a2 = last ? nA : cA + (size_t)(t + 2) * kstep; const char* b2 = last ? nB : cB + (size_t)(t + 2) * kstep;
;             const char* a3 = a2 + kstep; const char* b3 = b2 + kstep;
;     ...
;         for (int a = 0; a < 2; ++a)
; #pragma unroll
;             for (int b = 0; b < 2; ++b)
; #pragma unroll
;                 for (int m = 0; m < 4; ++m)
; #pragma unroll
;                     for (int n = 0; n < 2; ++n) acc[a][b][m][n] = (f32x4){0.f, 0.f, 0.f, 0.f};
.LBB0_1096:
	s_add_i32 s13, s55, -2
	s_add_u32 s59, s62, 0x100
	v_mov_b32_e32 v2, 0
	s_addc_u32 s69, s63, 0
	s_mov_b32 s64, 0
	v_mov_b32_e32 v3, v2
	v_mov_b32_e32 v4, v2
	v_mov_b32_e32 v5, v2
	v_mov_b32_e32 v6, v2
	v_mov_b32_e32 v7, v2
	v_mov_b32_e32 v8, v2
	v_mov_b32_e32 v9, v2
	v_mov_b32_e32 v18, v2
	v_mov_b32_e32 v19, v2
	v_mov_b32_e32 v20, v2
	v_mov_b32_e32 v21, v2
	v_mov_b32_e32 v22, v2
	v_mov_b32_e32 v23, v2
	v_mov_b32_e32 v24, v2
	v_mov_b32_e32 v25, v2
	v_mov_b32_e32 v34, v2
	v_mov_b32_e32 v35, v2
	v_mov_b32_e32 v36, v2
	v_mov_b32_e32 v37, v2
	v_mov_b32_e32 v38, v2
	v_mov_b32_e32 v39, v2
	v_mov_b32_e32 v40, v2
	v_mov_b32_e32 v41, v2
	v_mov_b32_e32 v50, v2
	v_mov_b32_e32 v51, v2
	v_mov_b32_e32 v52, v2
	v_mov_b32_e32 v53, v2
	v_mov_b32_e32 v54, v2
	v_mov_b32_e32 v55, v2
	v_mov_b32_e32 v56, v2
	v_mov_b32_e32 v57, v2
	v_mov_b32_e32 v10, v2
	v_mov_b32_e32 v11, v2
	v_mov_b32_e32 v12, v2
	v_mov_b32_e32 v13, v2
	v_mov_b32_e32 v14, v2
	v_mov_b32_e32 v15, v2
	v_mov_b32_e32 v16, v2
	v_mov_b32_e32 v17, v2
	v_mov_b32_e32 v26, v2
	v_mov_b32_e32 v27, v2
	v_mov_b32_e32 v28, v2
	v_mov_b32_e32 v29, v2
	v_mov_b32_e32 v30, v2
	v_mov_b32_e32 v31, v2
	v_mov_b32_e32 v32, v2
	v_mov_b32_e32 v33, v2
	v_mov_b32_e32 v42, v2
	v_mov_b32_e32 v43, v2
	v_mov_b32_e32 v44, v2
	v_mov_b32_e32 v45, v2
	v_mov_b32_e32 v46, v2
	v_mov_b32_e32 v47, v2
	v_mov_b32_e32 v48, v2
	v_mov_b32_e32 v49, v2
	v_mov_b32_e32 v58, v2
	v_mov_b32_e32 v59, v2
	v_mov_b32_e32 v60, v2
	v_mov_b32_e32 v61, v2
	v_mov_b32_e32 v62, v2
	v_mov_b32_e32 v63, v2
	v_mov_b32_e32 v64, v2
	v_mov_b32_e32 v65, v2
	v_mov_b32_e32 v66, v2
	v_mov_b32_e32 v67, v2
	v_mov_b32_e32 v68, v2
	v_mov_b32_e32 v69, v2
	v_mov_b32_e32 v70, v2
	v_mov_b32_e32 v71, v2
	v_mov_b32_e32 v72, v2
	v_mov_b32_e32 v73, v2
	v_mov_b32_e32 v82, v2
	v_mov_b32_e32 v83, v2
	v_mov_b32_e32 v84, v2
	v_mov_b32_e32 v85, v2
	v_mov_b32_e32 v86, v2
	v_mov_b32_e32 v87, v2
	v_mov_b32_e32 v88, v2
	v_mov_b32_e32 v89, v2
	v_mov_b32_e32 v98, v2
	v_mov_b32_e32 v99, v2
	v_mov_b32_e32 v100, v2
	v_mov_b32_e32 v101, v2
	v_mov_b32_e32 v102, v2
	v_mov_b32_e32 v103, v2
	v_mov_b32_e32 v104, v2
	v_mov_b32_e32 v105, v2
	v_mov_b32_e32 v114, v2
	v_mov_b32_e32 v115, v2
	v_mov_b32_e32 v116, v2
	v_mov_b32_e32 v117, v2
	v_mov_b32_e32 v118, v2
	v_mov_b32_e32 v119, v2
	v_mov_b32_e32 v120, v2
	v_mov_b32_e32 v121, v2
	v_mov_b32_e32 v74, v2
	v_mov_b32_e32 v75, v2
	v_mov_b32_e32 v76, v2
	v_mov_b32_e32 v77, v2
	v_mov_b32_e32 v78, v2
	v_mov_b32_e32 v79, v2
	v_mov_b32_e32 v80, v2
	v_mov_b32_e32 v81, v2
	v_mov_b32_e32 v90, v2
	v_mov_b32_e32 v91, v2
	v_mov_b32_e32 v92, v2
	v_mov_b32_e32 v93, v2
	v_mov_b32_e32 v94, v2
	v_mov_b32_e32 v95, v2
	v_mov_b32_e32 v96, v2
	v_mov_b32_e32 v97, v2
	v_mov_b32_e32 v106, v2
	v_mov_b32_e32 v107, v2
	v_mov_b32_e32 v108, v2
	v_mov_b32_e32 v109, v2
	v_mov_b32_e32 v110, v2
	v_mov_b32_e32 v111, v2
	v_mov_b32_e32 v112, v2
	v_mov_b32_e32 v113, v2
	v_mov_b32_e32 v122, v2
	v_mov_b32_e32 v123, v2
	v_mov_b32_e32 v124, v2
	v_mov_b32_e32 v125, v2
	v_mov_b32_e32 v126, v2
	v_mov_b32_e32 v127, v2
	v_mov_b32_e32 v128, v2
	v_mov_b32_e32 v129, v2
	s_cmp_lg_u32 s10, 0
	s_cbranch_scc1 .Lsprio_skip_4
	s_setprio 1

; #define PG8_STAGE(bufoff, gbase, voff) do { _Pragma("unroll") for (int _i = 0; _i < 2; ++_i) \
;         __builtin_amdgcn_global_load_lds((const unsigned*)((const char*)(gbase) + (voff)[_i]), (LAS unsigned*)(lds + (bufoff) + ldsw + _i * 8192), 16, 0, 0); } while (0)
; #define PG8_LDA(dst, b, h) do { _Pragma("unroll") for (int m = 0; m < 4; ++m) _Pragma("unroll") for (int k = 0; k < 2; ++k) dst[m][k] = *(const LAS bf16x8*)(lds + PG8_SA(b, h) + aoff + m * 2048 + k * 1024); } while (0)
; #define PG8_LDB(dst, b, h) do { _Pragma("unroll") for (int n = 0; n < 2; ++n) _Pragma("unroll") for (int k = 0; k < 2; ++k) dst[n][k] = *(const LAS bf16x8*)(lds + PG8_SB(b, h) + boff + n * 2048 + k * 1024); } while (0)
; #define PG8_MMA(ai, bj, At, Bt) do { __builtin_amdgcn_s_setprio(1); _Pragma("unroll") for (int m = 0; m < 4; ++m) _Pragma("unroll") for (int n = 0; n < 2; ++n) _Pragma("unroll") for (int k = 0; k < 2; ++k) \
;         acc[ai][bj][m][n] = __builtin_amdgcn_mfma_f32_16x16x32_bf16(Bt[n][k], At[m][k], acc[ai][bj][m][n], 0, 0, 0); __builtin_amdgcn_s_setprio(0); } while (0)
; #define PG8_WAIT_V(n) asm volatile("s_waitcnt vmcnt(" #n ")" ::: "memory")
; #define PG8_WAIT_L(n) asm volatile("s_waitcnt lgkmcnt(" #n ")" ::: "memory")
; #define PG8_BAR __builtin_amdgcn_s_barrier()
; #define PG8_SCHED __builtin_amdgcn_sched_barrier(0)
; template <class Epi, bool ALIGN_EPI = true, bool SP2 = true>
; __device__ __forceinline__ void gemm_phase(LAS unsigned char* lds, const Gemm g, const Order& S, const Epi& E) {
;     ...
;             const bool last = (t == nt - 2);
;             const char* a1 = cA + (size_t)(t + 1) * kstep;
;             const char* a2 = last ? nA : cA + (size_t)(t + 2) * kstep; const char* b2 = last ? nB : cB + (size_t)(t + 2) * kstep;
;             const char* a3 = a2 + kstep; const char* b3 = b2 + kstep;
;             if constexpr (SP2) {
;             PG8_LDB(B0, 0, 0); PG8_LDB(B1, 0, 1); PG8_SCHED; PG8_LDA(At, 0, 0); PG8_STAGE(PG8_SA(1, 1), a1 + hstepA, voffA);
;             PG8_WAIT_V(8); PG8_WAIT_L(0); PG8_BAR; PG8_MMA(0, 0, At, B0); PG8_MMA(0, 1, At, B1); PG8_BAR; PG8_SCHED;
;             PG8_LDA(At, 0, 1); PG8_STAGE(PG8_SB(0, 0), b2, voffB); PG8_STAGE(PG8_SB(0, 1), b2 + hstepB, voffB); PG8_STAGE(PG8_SA(0, 0), a2, voffA);
;             PG8_WAIT_V(8); PG8_WAIT_L(0); PG8_BAR; PG8_MMA(1, 0, At, B0); PG8_MMA(1, 1, At, B1); PG8_BAR; PG8_SCHED;
.LBB0_1097:
	s_add_i32 s70, s64, 2
	s_add_u32 s62, s60, 0x100
	s_addc_u32 s63, s61, 0
	s_add_i32 s71, 0, 0x10000
	s_cmp_eq_u32 s13, s64
	s_cselect_b32 s67, s15, s63
	s_cselect_b32 s66, s14, s62
	v_add_u32_e32 v158, s71, v160
	s_cselect_b32 s65, s57, s69
	s_cselect_b32 s64, s56, s59
	s_add_i32 s72, 0, 0x14000
	ds_read_b128 v[162:165], v158
	ds_read_b128 v[166:169], v158 offset:1024
	ds_read_b128 v[170:173], v158 offset:2048
	ds_read_b128 v[174:177], v158 offset:3072
	v_add_u32_e32 v158, s72, v160
	ds_read_b128 v[178:181], v158
	ds_read_b128 v[182:185], v158 offset:1024
	ds_read_b128 v[186:189], v158 offset:2048
	ds_read_b128 v[190:193], v158 offset:3072
	v_lshl_add_u64 v[158:159], s[60:61], 0, v[154:155]
	s_add_i32 m0, s35, 0xc000
	ds_read_b128 v[194:197], v161
	ds_read_b128 v[198:201], v161 offset:1024
	ds_read_b128 v[224:227], v161 offset:2048
	ds_read_b128 v[228:231], v161 offset:3072
	ds_read_b128 v[232:235], v161 offset:4096
	ds_read_b128 v[236:239], v161 offset:5120
	ds_read_b128 v[240:243], v161 offset:6144
	ds_read_b128 v[244:247], v161 offset:7168
	global_load_lds_dwordx4 v[158:159], off
	v_lshl_add_u64 v[158:159], s[60:61], 0, v[156:157]
	s_add_i32 m0, s35, 0xe000
	s_nop 0
	global_load_lds_dwordx4 v[158:159], off
	s_waitcnt vmcnt(8)
	s_waitcnt lgkmcnt(0)
	s_barrier
	s_waitcnt lgkmcnt(0)
	v_mfma_f32_16x16x32_bf16 v[126:129], v[162:165], v[194:197], v[126:129]
	v_mfma_f32_16x16x32_bf16 v[122:125], v[170:173], v[194:197], v[122:125]
	v_mfma_f32_16x16x32_bf16 v[110:113], v[162:165], v[224:227], v[110:113]
	v_mfma_f32_16x16x32_bf16 v[106:109], v[170:173], v[224:227], v[106:109]
	v_mfma_f32_16x16x32_bf16 v[94:97], v[162:165], v[232:235], v[94:97]
	v_mfma_f32_16x16x32_bf16 v[90:93], v[170:173], v[232:235], v[90:93]
	v_mfma_f32_16x16x32_bf16 v[78:81], v[162:165], v[240:243], v[78:81]
	v_mfma_f32_16x16x32_bf16 v[74:77], v[170:173], v[240:243], v[74:77]
	v_mfma_f32_16x16x32_bf16 v[126:129], v[166:169], v[198:201], v[126:129]
	v_mfma_f32_16x16x32_bf16 v[122:125], v[174:177], v[198:201], v[122:125]
	v_mfma_f32_16x16x32_bf16 v[110:113], v[166:169], v[228:231], v[110:113]
	v_mfma_f32_16x16x32_bf16 v[106:109], v[174:177], v[228:231], v[106:109]
	v_mfma_f32_16x16x32_bf16 v[94:97], v[166:169], v[236:239], v[94:97]
	v_mfma_f32_16x16x32_bf16 v[90:93], v[174:177], v[236:239], v[90:93]
	v_mfma_f32_16x16x32_bf16 v[78:81], v[166:169], v[244:247], v[78:81]
	v_mfma_f32_16x16x32_bf16 v[74:77], v[174:177], v[244:247], v[74:77]
	v_mfma_f32_16x16x32_bf16 v[118:121], v[178:181], v[194:197], v[118:121]
	v_mfma_f32_16x16x32_bf16 v[114:117], v[186:189], v[194:197], v[114:117]
	v_mfma_f32_16x16x32_bf16 v[102:105], v[178:181], v[224:227], v[102:105]
	v_mfma_f32_16x16x32_bf16 v[98:101], v[186:189], v[224:227], v[98:101]
	v_mfma_f32_16x16x32_bf16 v[86:89], v[178:181], v[232:235], v[86:89]
	v_mfma_f32_16x16x32_bf16 v[82:85], v[186:189], v[232:235], v[82:85]
	v_mfma_f32_16x16x32_bf16 v[70:73], v[178:181], v[240:243], v[70:73]
	v_mfma_f32_16x16x32_bf16 v[66:69], v[186:189], v[240:243], v[66:69]
	v_mfma_f32_16x16x32_bf16 v[118:121], v[182:185], v[198:201], v[118:121]
	v_mfma_f32_16x16x32_bf16 v[114:117], v[190:193], v[198:201], v[114:117]
	v_mfma_f32_16x16x32_bf16 v[102:105], v[182:185], v[228:231], v[102:105]
	v_mfma_f32_16x16x32_bf16 v[98:101], v[190:193], v[228:231], v[98:101]
	v_mfma_f32_16x16x32_bf16 v[86:89], v[182:185], v[236:239], v[86:89]
	v_mfma_f32_16x16x32_bf16 v[82:85], v[190:193], v[236:239], v[82:85]
	v_mfma_f32_16x16x32_bf16 v[70:73], v[182:185], v[244:247], v[70:73]
	v_mfma_f32_16x16x32_bf16 v[66:69], v[190:193], v[244:247], v[66:69]
	s_barrier
	s_add_i32 s60, s71, s21
	v_lshl_add_u64 v[158:159], s[64:65], 0, v[0:1]
	s_mov_b32 m0, s60
	ds_read_b128 v[194:197], v161 offset:16384
	ds_read_b128 v[198:201], v161 offset:17408
	ds_read_b128 v[224:227], v161 offset:18432
	ds_read_b128 v[228:231], v161 offset:19456
	ds_read_b128 v[232:235], v161 offset:20480
	ds_read_b128 v[236:239], v161 offset:21504
	ds_read_b128 v[240:243], v161 offset:22528
	ds_read_b128 v[244:247], v161 offset:23552
	global_load_lds_dwordx4 v[158:159], off
	s_add_i32 m0, s60, 0x2000
	s_add_u32 s60, s64, 0xb0000
	v_lshl_add_u64 v[202:203], s[64:65], 0, v[134:135]
	s_addc_u32 s61, s65, 0
	s_add_i32 s71, s72, s21
	global_load_lds_dwordx4 v[202:203], off
	v_lshl_add_u64 v[210:211], s[60:61], 0, v[0:1]
	s_mov_b32 m0, s71
	v_lshl_add_u64 v[248:249], s[66:67], 0, v[132:133]
	global_load_lds_dwordx4 v[210:211], off
	v_lshl_add_u64 v[210:211], s[60:61], 0, v[134:135]
	s_add_i32 m0, s71, 0x2000
	s_nop 0
	global_load_lds_dwordx4 v[210:211], off
	v_lshl_add_u64 v[210:211], s[66:67], 0, v[130:131]
	s_mov_b32 m0, s35
	s_nop 0
	global_load_lds_dwordx4 v[210:211], off
	s_mov_b32 m0, s40
	s_nop 0
	global_load_lds_dwordx4 v[248:249], off
	s_waitcnt vmcnt(8)
	s_waitcnt lgkmcnt(0)
	s_barrier
; #define PG8_STAGE(bufoff, gbase, voff) do { _Pragma("unroll") for (int _i = 0; _i < 2; ++_i) \
;         __builtin_amdgcn_global_load_lds((const unsigned*)((const char*)(gbase) + (voff)[_i]), (LAS unsigned*)(lds + (bufoff) + ldsw + _i * 8192), 16, 0, 0); } while (0)
; #define PG8_LDA(dst, b, h) do { _Pragma("unroll") for (int m = 0; m < 4; ++m) _Pragma("unroll") for (int k = 0; k < 2; ++k) dst[m][k] = *(const LAS bf16x8*)(lds + PG8_SA(b, h) + aoff + m * 2048 + k * 1024); } while (0)
; #define PG8_LDB(dst, b, h) do { _Pragma("unroll") for (int n = 0; n < 2; ++n) _Pragma("unroll") for (int k = 0; k < 2; ++k) dst[n][k] = *(const LAS bf16x8*)(lds + PG8_SB(b, h) + boff + n * 2048 + k * 1024); } while (0)
; #define PG8_MMA(ai, bj, At, Bt) do { __builtin_amdgcn_s_setprio(1); _Pragma("unroll") for (int m = 0; m < 4; ++m) _Pragma("unroll") for (int n = 0; n < 2; ++n) _Pragma("unroll") for (int k = 0; k < 2; ++k) \
;         acc[ai][bj][m][n] = __builtin_amdgcn_mfma_f32_16x16x32_bf16(Bt[n][k], At[m][k], acc[ai][bj][m][n], 0, 0, 0); __builtin_amdgcn_s_setprio(0); } while (0)
; #define PG8_WAIT_V(n) asm volatile("s_waitcnt vmcnt(" #n ")" ::: "memory")
; #define PG8_WAIT_L(n) asm volatile("s_waitcnt lgkmcnt(" #n ")" ::: "memory")
; #define PG8_BAR __builtin_amdgcn_s_barrier()
; #define PG8_SCHED __builtin_amdgcn_sched_barrier(0)
; template <class Epi, bool ALIGN_EPI = true, bool SP2 = true>
; __device__ __forceinline__ void gemm_phase(LAS unsigned char* lds, const Gemm g, const Order& S, const Epi& E) {
;     ...
;             PG8_WAIT_V(8); PG8_WAIT_L(0); PG8_BAR; PG8_MMA(1, 0, At, B0); PG8_MMA(1, 1, At, B1); PG8_BAR; PG8_SCHED;
;             PG8_LDB(B0, 1, 0); PG8_LDB(B1, 1, 1); PG8_SCHED; PG8_LDA(At, 1, 0); PG8_STAGE(PG8_SA(0, 1), a2 + hstepA, voffA);
;             PG8_WAIT_V(8); PG8_WAIT_L(0); PG8_BAR; PG8_MMA(0, 0, At, B0); PG8_MMA(0, 1, At, B1); PG8_BAR; PG8_SCHED;
	s_waitcnt lgkmcnt(0)
	v_mfma_f32_16x16x32_bf16 v[62:65], v[162:165], v[194:197], v[62:65]
	v_mfma_f32_16x16x32_bf16 v[58:61], v[170:173], v[194:197], v[58:61]
	v_mfma_f32_16x16x32_bf16 v[46:49], v[162:165], v[224:227], v[46:49]
	v_mfma_f32_16x16x32_bf16 v[42:45], v[170:173], v[224:227], v[42:45]
	v_mfma_f32_16x16x32_bf16 v[30:33], v[162:165], v[232:235], v[30:33]
	v_mfma_f32_16x16x32_bf16 v[26:29], v[170:173], v[232:235], v[26:29]
	v_mfma_f32_16x16x32_bf16 v[14:17], v[162:165], v[240:243], v[14:17]
	v_mfma_f32_16x16x32_bf16 v[10:13], v[170:173], v[240:243], v[10:13]
	v_mfma_f32_16x16x32_bf16 v[62:65], v[166:169], v[198:201], v[62:65]
	v_mfma_f32_16x16x32_bf16 v[58:61], v[174:177], v[198:201], v[58:61]
	v_mfma_f32_16x16x32_bf16 v[46:49], v[166:169], v[228:231], v[46:49]
	v_mfma_f32_16x16x32_bf16 v[42:45], v[174:177], v[228:231], v[42:45]
	v_mfma_f32_16x16x32_bf16 v[30:33], v[166:169], v[236:239], v[30:33]
	v_mfma_f32_16x16x32_bf16 v[26:29], v[174:177], v[236:239], v[26:29]
	v_mfma_f32_16x16x32_bf16 v[14:17], v[166:169], v[244:247], v[14:17]
	v_mfma_f32_16x16x32_bf16 v[10:13], v[174:177], v[244:247], v[10:13]
	v_mfma_f32_16x16x32_bf16 v[54:57], v[178:181], v[194:197], v[54:57]
	v_mfma_f32_16x16x32_bf16 v[50:53], v[186:189], v[194:197], v[50:53]
	v_mfma_f32_16x16x32_bf16 v[38:41], v[178:181], v[224:227], v[38:41]
	v_mfma_f32_16x16x32_bf16 v[34:37], v[186:189], v[224:227], v[34:37]
	v_mfma_f32_16x16x32_bf16 v[22:25], v[178:181], v[232:235], v[22:25]
	v_mfma_f32_16x16x32_bf16 v[18:21], v[186:189], v[232:235], v[18:21]
	v_mfma_f32_16x16x32_bf16 v[6:9], v[178:181], v[240:243], v[6:9]
	v_mfma_f32_16x16x32_bf16 v[2:5], v[186:189], v[240:243], v[2:5]
	v_mfma_f32_16x16x32_bf16 v[54:57], v[182:185], v[198:201], v[54:57]
	v_mfma_f32_16x16x32_bf16 v[50:53], v[190:193], v[198:201], v[50:53]
	v_mfma_f32_16x16x32_bf16 v[38:41], v[182:185], v[228:231], v[38:41]
	v_mfma_f32_16x16x32_bf16 v[34:37], v[190:193], v[228:231], v[34:37]
	v_mfma_f32_16x16x32_bf16 v[22:25], v[182:185], v[236:239], v[22:25]
	v_mfma_f32_16x16x32_bf16 v[18:21], v[190:193], v[236:239], v[18:21]
	v_mfma_f32_16x16x32_bf16 v[6:9], v[182:185], v[244:247], v[6:9]
	v_mfma_f32_16x16x32_bf16 v[2:5], v[190:193], v[244:247], v[2:5]
	s_barrier
	s_add_i32 s71, 0, 0x18000
	s_add_i32 s72, 0, 0x1c000
	v_add_u32_e32 v174, s71, v160
	v_add_u32_e32 v190, s72, v160
	ds_read_b128 v[162:165], v174
	ds_read_b128 v[166:169], v174 offset:1024
	ds_read_b128 v[170:173], v174 offset:2048
	ds_read_b128 v[174:177], v174 offset:3072
	ds_read_b128 v[178:181], v190
	ds_read_b128 v[182:185], v190 offset:1024
	ds_read_b128 v[186:189], v190 offset:2048
	ds_read_b128 v[190:193], v190 offset:3072
	s_add_u32 s60, s66, 0xb0000
	s_addc_u32 s61, s67, 0
	s_mov_b32 m0, s42
	v_lshl_add_u64 v[250:251], s[60:61], 0, v[130:131]
	ds_read_b128 v[194:197], v161 offset:32768
	ds_read_b128 v[198:201], v161 offset:33792
	ds_read_b128 v[224:227], v161 offset:34816
	ds_read_b128 v[228:231], v161 offset:35840
	ds_read_b128 v[232:235], v161 offset:36864
	ds_read_b128 v[236:239], v161 offset:37888
	ds_read_b128 v[240:243], v161 offset:38912
	ds_read_b128 v[244:247], v161 offset:39936
	global_load_lds_dwordx4 v[250:251], off
	v_lshl_add_u64 v[250:251], s[60:61], 0, v[132:133]
	s_mov_b32 m0, s44
	s_nop 0
	global_load_lds_dwordx4 v[250:251], off
	s_waitcnt vmcnt(8)
	s_waitcnt lgkmcnt(0)
	s_barrier
	s_waitcnt lgkmcnt(0)
	v_mfma_f32_16x16x32_bf16 v[126:129], v[162:165], v[194:197], v[126:129]
	v_mfma_f32_16x16x32_bf16 v[122:125], v[170:173], v[194:197], v[122:125]
	v_mfma_f32_16x16x32_bf16 v[110:113], v[162:165], v[224:227], v[110:113]
	v_mfma_f32_16x16x32_bf16 v[106:109], v[170:173], v[224:227], v[106:109]
	v_mfma_f32_16x16x32_bf16 v[94:97], v[162:165], v[232:235], v[94:97]
	v_mfma_f32_16x16x32_bf16 v[90:93], v[170:173], v[232:235], v[90:93]
	v_mfma_f32_16x16x32_bf16 v[78:81], v[162:165], v[240:243], v[78:81]
	v_mfma_f32_16x16x32_bf16 v[74:77], v[170:173], v[240:243], v[74:77]
	v_mfma_f32_16x16x32_bf16 v[126:129], v[166:169], v[198:201], v[126:129]
	v_mfma_f32_16x16x32_bf16 v[122:125], v[174:177], v[198:201], v[122:125]
	v_mfma_f32_16x16x32_bf16 v[110:113], v[166:169], v[228:231], v[110:113]
	v_mfma_f32_16x16x32_bf16 v[106:109], v[174:177], v[228:231], v[106:109]
	v_mfma_f32_16x16x32_bf16 v[94:97], v[166:169], v[236:239], v[94:97]
	v_mfma_f32_16x16x32_bf16 v[90:93], v[174:177], v[236:239], v[90:93]
	v_mfma_f32_16x16x32_bf16 v[78:81], v[166:169], v[244:247], v[78:81]
	v_mfma_f32_16x16x32_bf16 v[74:77], v[174:177], v[244:247], v[74:77]
	v_mfma_f32_16x16x32_bf16 v[118:121], v[178:181], v[194:197], v[118:121]
	v_mfma_f32_16x16x32_bf16 v[114:117], v[186:189], v[194:197], v[114:117]
	v_mfma_f32_16x16x32_bf16 v[102:105], v[178:181], v[224:227], v[102:105]
	v_mfma_f32_16x16x32_bf16 v[98:101], v[186:189], v[224:227], v[98:101]
	v_mfma_f32_16x16x32_bf16 v[86:89], v[178:181], v[232:235], v[86:89]
	v_mfma_f32_16x16x32_bf16 v[82:85], v[186:189], v[232:235], v[82:85]
	v_mfma_f32_16x16x32_bf16 v[70:73], v[178:181], v[240:243], v[70:73]
	v_mfma_f32_16x16x32_bf16 v[66:69], v[186:189], v[240:243], v[66:69]
	v_mfma_f32_16x16x32_bf16 v[118:121], v[182:185], v[198:201], v[118:121]
	v_mfma_f32_16x16x32_bf16 v[114:117], v[190:193], v[198:201], v[114:117]
	v_mfma_f32_16x16x32_bf16 v[102:105], v[182:185], v[228:231], v[102:105]
	v_mfma_f32_16x16x32_bf16 v[98:101], v[190:193], v[228:231], v[98:101]
	v_mfma_f32_16x16x32_bf16 v[86:89], v[182:185], v[236:239], v[86:89]
	v_mfma_f32_16x16x32_bf16 v[82:85], v[190:193], v[236:239], v[82:85]
	v_mfma_f32_16x16x32_bf16 v[70:73], v[182:185], v[244:247], v[70:73]
	v_mfma_f32_16x16x32_bf16 v[66:69], v[190:193], v[244:247], v[66:69]
	s_barrier
; #define PG8_STAGE(bufoff, gbase, voff) do { _Pragma("unroll") for (int _i = 0; _i < 2; ++_i) \
;         __builtin_amdgcn_global_load_lds((const unsigned*)((const char*)(gbase) + (voff)[_i]), (LAS unsigned*)(lds + (bufoff) + ldsw + _i * 8192), 16, 0, 0); } while (0)
; #define PG8_LDA(dst, b, h) do { _Pragma("unroll") for (int m = 0; m < 4; ++m) _Pragma("unroll") for (int k = 0; k < 2; ++k) dst[m][k] = *(const LAS bf16x8*)(lds + PG8_SA(b, h) + aoff + m * 2048 + k * 1024); } while (0)
; #define PG8_MMA(ai, bj, At, Bt) do { __builtin_amdgcn_s_setprio(1); _Pragma("unroll") for (int m = 0; m < 4; ++m) _Pragma("unroll") for (int n = 0; n < 2; ++n) _Pragma("unroll") for (int k = 0; k < 2; ++k) \
;         acc[ai][bj][m][n] = __builtin_amdgcn_mfma_f32_16x16x32_bf16(Bt[n][k], At[m][k], acc[ai][bj][m][n], 0, 0, 0); __builtin_amdgcn_s_setprio(0); } while (0)
; #define PG8_WAIT_V(n) asm volatile("s_waitcnt vmcnt(" #n ")" ::: "memory")
; #define PG8_WAIT_L(n) asm volatile("s_waitcnt lgkmcnt(" #n ")" ::: "memory")
; #define PG8_BAR __builtin_amdgcn_s_barrier()
; #define PG8_SCHED __builtin_amdgcn_sched_barrier(0)
; template <class Epi, bool ALIGN_EPI = true, bool SP2 = true>
; __device__ __forceinline__ void gemm_phase(LAS unsigned char* lds, const Gemm g, const Order& S, const Epi& E) {
;     ...
;             PG8_LDA(At, 1, 1); PG8_STAGE(PG8_SB(1, 0), b3, voffB); PG8_STAGE(PG8_SB(1, 1), b3 + hstepB, voffB); PG8_STAGE(PG8_SA(1, 0), a3, voffA);
;             PG8_WAIT_V(8); PG8_WAIT_L(0); PG8_BAR; PG8_MMA(1, 0, At, B0); PG8_MMA(1, 1, At, B1); PG8_BAR; PG8_SCHED;
;     ...
;         if constexpr (ALIGN_EPI) { if (wr == 0) PG8_BAR; }
	s_add_i32 s60, s71, s21
	v_lshl_add_u64 v[158:159], v[158:159], 0, s[26:27]
	s_mov_b32 m0, s60
	ds_read_b128 v[194:197], v161 offset:49152
	ds_read_b128 v[198:201], v161 offset:50176
	ds_read_b128 v[224:227], v161 offset:51200
	ds_read_b128 v[228:231], v161 offset:52224
	ds_read_b128 v[232:235], v161 offset:53248
	ds_read_b128 v[236:239], v161 offset:54272
	ds_read_b128 v[240:243], v161 offset:55296
	ds_read_b128 v[244:247], v161 offset:56320
	global_load_lds_dwordx4 v[158:159], off
	s_add_i32 m0, s60, 0x2000
	s_add_u32 s60, s64, 0xb0080
	v_lshl_add_u64 v[158:159], v[202:203], 0, s[26:27]
	s_addc_u32 s61, s65, 0
	s_add_i32 s64, s72, s21
	global_load_lds_dwordx4 v[158:159], off
	v_lshl_add_u64 v[158:159], s[60:61], 0, v[0:1]
	s_mov_b32 m0, s64
	s_nop 0
	global_load_lds_dwordx4 v[158:159], off
	v_lshl_add_u64 v[158:159], s[60:61], 0, v[134:135]
	s_add_i32 m0, s64, 0x2000
	s_nop 0
	global_load_lds_dwordx4 v[158:159], off
	v_lshl_add_u64 v[158:159], v[210:211], 0, s[26:27]
	s_mov_b32 m0, s48
	s_nop 0
	global_load_lds_dwordx4 v[158:159], off
	v_lshl_add_u64 v[158:159], v[248:249], 0, s[26:27]
	s_mov_b32 m0, s49
	s_nop 0
	global_load_lds_dwordx4 v[158:159], off
	s_waitcnt vmcnt(8)
	s_waitcnt lgkmcnt(0)
	s_barrier
	s_waitcnt lgkmcnt(0)
	v_mfma_f32_16x16x32_bf16 v[62:65], v[162:165], v[194:197], v[62:65]
	v_mfma_f32_16x16x32_bf16 v[58:61], v[170:173], v[194:197], v[58:61]
	v_mfma_f32_16x16x32_bf16 v[46:49], v[162:165], v[224:227], v[46:49]
	v_mfma_f32_16x16x32_bf16 v[42:45], v[170:173], v[224:227], v[42:45]
	v_mfma_f32_16x16x32_bf16 v[30:33], v[162:165], v[232:235], v[30:33]
	v_mfma_f32_16x16x32_bf16 v[26:29], v[170:173], v[232:235], v[26:29]
	v_mfma_f32_16x16x32_bf16 v[14:17], v[162:165], v[240:243], v[14:17]
	v_mfma_f32_16x16x32_bf16 v[10:13], v[170:173], v[240:243], v[10:13]
	v_mfma_f32_16x16x32_bf16 v[62:65], v[166:169], v[198:201], v[62:65]
	v_mfma_f32_16x16x32_bf16 v[58:61], v[174:177], v[198:201], v[58:61]
	v_mfma_f32_16x16x32_bf16 v[46:49], v[166:169], v[228:231], v[46:49]
	v_mfma_f32_16x16x32_bf16 v[42:45], v[174:177], v[228:231], v[42:45]
	v_mfma_f32_16x16x32_bf16 v[30:33], v[166:169], v[236:239], v[30:33]
	v_mfma_f32_16x16x32_bf16 v[26:29], v[174:177], v[236:239], v[26:29]
	v_mfma_f32_16x16x32_bf16 v[14:17], v[166:169], v[244:247], v[14:17]
	v_mfma_f32_16x16x32_bf16 v[10:13], v[174:177], v[244:247], v[10:13]
	v_mfma_f32_16x16x32_bf16 v[54:57], v[178:181], v[194:197], v[54:57]
	v_mfma_f32_16x16x32_bf16 v[50:53], v[186:189], v[194:197], v[50:53]
	v_mfma_f32_16x16x32_bf16 v[38:41], v[178:181], v[224:227], v[38:41]
	v_mfma_f32_16x16x32_bf16 v[34:37], v[186:189], v[224:227], v[34:37]
	v_mfma_f32_16x16x32_bf16 v[22:25], v[178:181], v[232:235], v[22:25]
	v_mfma_f32_16x16x32_bf16 v[18:21], v[186:189], v[232:235], v[18:21]
	v_mfma_f32_16x16x32_bf16 v[6:9], v[178:181], v[240:243], v[6:9]
	v_mfma_f32_16x16x32_bf16 v[2:5], v[186:189], v[240:243], v[2:5]
	v_mfma_f32_16x16x32_bf16 v[54:57], v[182:185], v[198:201], v[54:57]
	v_mfma_f32_16x16x32_bf16 v[50:53], v[190:193], v[198:201], v[50:53]
	v_mfma_f32_16x16x32_bf16 v[38:41], v[182:185], v[228:231], v[38:41]
	v_mfma_f32_16x16x32_bf16 v[34:37], v[190:193], v[228:231], v[34:37]
	v_mfma_f32_16x16x32_bf16 v[22:25], v[182:185], v[236:239], v[22:25]
	v_mfma_f32_16x16x32_bf16 v[18:21], v[190:193], v[236:239], v[18:21]
	v_mfma_f32_16x16x32_bf16 v[6:9], v[182:185], v[244:247], v[6:9]
	v_mfma_f32_16x16x32_bf16 v[2:5], v[190:193], v[244:247], v[2:5]
	s_barrier
	s_add_u32 s59, s59, 0x100
	s_addc_u32 s69, s69, 0
	s_cmp_ge_i32 s70, s55
	s_mov_b64 s[60:61], s[62:63]
	s_mov_b32 s64, s70
	s_cbranch_scc0 .LBB0_1097
	s_setprio 0
	s_and_b64 vcc, exec, s[10:11]
	s_cbranch_vccz .LBB0_1105
